# baseline (speedup 1.0000x reference)
; #define STAGE(P, GP, ktrel) do { const GAS char* _g = (GP) + (ktrel) * (BK * 2); \
;     __builtin_amdgcn_global_load_lds((const GAS unsigned*)(_g + so0), (unsigned*)((char*)(P) + tid_ * 16), 16, 0, 0); \
;     __builtin_amdgcn_global_load_lds((const GAS unsigned*)(_g + so1), (unsigned*)((char*)(P) + tid_ * 16 + 8192), 16, 0, 0); } while (0)
; #define WAIT_L(n) asm volatile("s_waitcnt lgkmcnt(" #n ")" ::: "memory")
; #define BAR __builtin_amdgcn_s_barrier()
; #define SCHED __builtin_amdgcn_sched_barrier(0)
; #define LDA(dst, b, h) for (int m = 0; m < 4; ++m) for (int k = 0; k < 2; ++k) \
;     dst[m][k] = *reinterpret_cast<const bf16x8*>((char*)SA(b, h) + lds_byte(wr * 64 + m * 16 + fr, k * 32 + fq * 8))
; #define LDB(dst, b, h) for (int n = 0; n < 2; ++n) for (int k = 0; k < 2; ++k) \
;     dst[n][k] = *reinterpret_cast<const bf16x8*>((char*)SB(b, h) + lds_byte(wc * 32 + n * 16 + fr, k * 32 + fq * 8))
; #define MMA(ai, bj, At_, Bt_) do { __builtin_amdgcn_s_setprio(1); \
;     for (int m = 0; m < 4; ++m) for (int n = 0; n < 2; ++n) for (int k = 0; k < 2; ++k) \
;       acc[ai][bj][m][n] = __builtin_amdgcn_mfma_f32_16x16x32_bf16(At_[m][k], Bt_[n][k], acc[ai][bj][m][n], 0, 0, 0); \
;     __builtin_amdgcn_s_setprio(0); } while (0)
; template <int K, int LD = K>
; __device__ __forceinline__ void gemm_main(const GAS bf16* A, const GAS bf16* Bt, int brow, int bcol, f32x4 (&acc)[2][2][4][2]) {
;     ...
;   for (int t = 0; t < nt - 2; t += 2) {
;     LDB(B0, 0, 0); SCHED; LDA(At, 0, 0); STAGE(SA(1, 1), pA1, 1);
;     WAIT_L(8); BAR; WAIT_L(0); MMA(0, 0, At, B0); BAR; SCHED;
;     LDB(B1, 0, 1); STAGE(SB(0, 0), pB0, 2);
;     BAR; WAIT_L(0); MMA(0, 1, At, B1); BAR;
;     LDA(At, 0, 1); STAGE(SA(0, 0), pA0, 2);
;     BAR; WAIT_L(0); MMA(1, 0, At, B0); BAR; SCHED;
.LBB0_89:
	ds_read_b128 v[162:165], v144
	ds_read_b128 v[166:169], v144 offset:1024
	ds_read_b128 v[174:177], v144 offset:2048
	ds_read_b128 v[178:181], v144 offset:3072
	v_lshl_add_u64 v[230:231], s[14:15], 0, v[130:131]
	v_readfirstlane_b32 s24, v151
	v_lshl_add_u64 v[214:215], v[230:231], 0, s[8:9]
	s_mov_b32 m0, s24
	v_lshl_add_u64 v[232:233], s[14:15], 0, v[132:133]
	v_readfirstlane_b32 s24, v150
	ds_read_b128 v[182:185], v140
	ds_read_b128 v[186:189], v140 offset:1024
	ds_read_b128 v[190:193], v139
	ds_read_b128 v[194:197], v139 offset:1024
	ds_read_b128 v[198:201], v138
	ds_read_b128 v[202:205], v138 offset:1024
	ds_read_b128 v[206:209], v137
	ds_read_b128 v[210:213], v137 offset:1024
	global_load_lds_dwordx4 v[214:215], off
	v_lshl_add_u64 v[214:215], v[232:233], 0, s[8:9]
	s_mov_b32 m0, s24
	s_nop 0
	global_load_lds_dwordx4 v[214:215], off
	s_waitcnt lgkmcnt(8)
	s_waitcnt vmcnt(10)
	s_barrier
	s_waitcnt lgkmcnt(0)
	s_waitcnt lgkmcnt(0)
	v_mfma_f32_16x16x32_bf16 v[126:129], v[162:165], v[182:185], v[126:129]
	v_mfma_f32_16x16x32_bf16 v[122:125], v[174:177], v[182:185], v[122:125]
	v_mfma_f32_16x16x32_bf16 v[118:121], v[162:165], v[190:193], v[118:121]
	v_mfma_f32_16x16x32_bf16 v[114:117], v[174:177], v[190:193], v[114:117]
	v_mfma_f32_16x16x32_bf16 v[110:113], v[162:165], v[198:201], v[110:113]
	v_mfma_f32_16x16x32_bf16 v[106:109], v[174:177], v[198:201], v[106:109]
	v_mfma_f32_16x16x32_bf16 v[102:105], v[162:165], v[206:209], v[102:105]
	v_mfma_f32_16x16x32_bf16 v[98:101], v[174:177], v[206:209], v[98:101]
	v_mfma_f32_16x16x32_bf16 v[126:129], v[166:169], v[186:189], v[126:129]
	v_mfma_f32_16x16x32_bf16 v[122:125], v[178:181], v[186:189], v[122:125]
	v_mfma_f32_16x16x32_bf16 v[118:121], v[166:169], v[194:197], v[118:121]
	v_mfma_f32_16x16x32_bf16 v[114:117], v[178:181], v[194:197], v[114:117]
	v_mfma_f32_16x16x32_bf16 v[110:113], v[166:169], v[202:205], v[110:113]
	v_mfma_f32_16x16x32_bf16 v[106:109], v[178:181], v[202:205], v[106:109]
	v_mfma_f32_16x16x32_bf16 v[102:105], v[166:169], v[210:213], v[102:105]
	v_mfma_f32_16x16x32_bf16 v[98:101], v[178:181], v[210:213], v[98:101]
	s_barrier
	v_lshl_add_u64 v[234:235], s[22:23], 0, v[130:131]
	v_readfirstlane_b32 s24, v146
	v_lshl_add_u64 v[236:237], v[234:235], 0, s[10:11]
	s_mov_b32 m0, s24
	ds_read_b128 v[214:217], v143
	ds_read_b128 v[218:221], v143 offset:1024
	ds_read_b128 v[222:225], v143 offset:2048
	ds_read_b128 v[226:229], v143 offset:3072
	global_load_lds_dwordx4 v[236:237], off
	v_lshl_add_u64 v[236:237], s[22:23], 0, v[132:133]
	v_readfirstlane_b32 s24, v157
	v_lshl_add_u64 v[238:239], v[236:237], 0, s[10:11]
	s_mov_b32 m0, s24
	s_add_u32 s22, s22, 0x100
	global_load_lds_dwordx4 v[238:239], off
	s_waitcnt vmcnt(10)
	s_barrier
	s_waitcnt lgkmcnt(0)
	s_addc_u32 s23, s23, 0
	s_waitcnt lgkmcnt(0)
	v_mfma_f32_16x16x32_bf16 v[94:97], v[214:217], v[182:185], v[94:97]
	v_mfma_f32_16x16x32_bf16 v[90:93], v[222:225], v[182:185], v[90:93]
	v_mfma_f32_16x16x32_bf16 v[86:89], v[214:217], v[190:193], v[86:89]
	v_mfma_f32_16x16x32_bf16 v[82:85], v[222:225], v[190:193], v[82:85]
	v_mfma_f32_16x16x32_bf16 v[78:81], v[214:217], v[198:201], v[78:81]
	v_mfma_f32_16x16x32_bf16 v[74:77], v[222:225], v[198:201], v[74:77]
	v_mfma_f32_16x16x32_bf16 v[70:73], v[214:217], v[206:209], v[70:73]
	v_mfma_f32_16x16x32_bf16 v[66:69], v[222:225], v[206:209], v[66:69]
	v_mfma_f32_16x16x32_bf16 v[94:97], v[218:221], v[186:189], v[94:97]
	v_mfma_f32_16x16x32_bf16 v[90:93], v[226:229], v[186:189], v[90:93]
	v_mfma_f32_16x16x32_bf16 v[86:89], v[218:221], v[194:197], v[86:89]
	v_mfma_f32_16x16x32_bf16 v[82:85], v[226:229], v[194:197], v[82:85]
	v_mfma_f32_16x16x32_bf16 v[78:81], v[218:221], v[202:205], v[78:81]
	v_mfma_f32_16x16x32_bf16 v[74:77], v[226:229], v[202:205], v[74:77]
	v_mfma_f32_16x16x32_bf16 v[70:73], v[218:221], v[210:213], v[70:73]
	v_mfma_f32_16x16x32_bf16 v[66:69], v[226:229], v[210:213], v[66:69]
	v_lshl_add_u64 v[238:239], s[20:21], 0, v[130:131]
	v_readfirstlane_b32 s24, v145
	v_lshl_add_u64 v[240:241], v[238:239], 0, s[10:11]
	s_mov_b32 m0, s24
	s_barrier
	ds_read_b128 v[182:185], v140 offset:16384
	ds_read_b128 v[186:189], v140 offset:17408
	ds_read_b128 v[190:193], v139 offset:16384
	ds_read_b128 v[194:197], v139 offset:17408
	ds_read_b128 v[198:201], v138 offset:16384
	ds_read_b128 v[202:205], v138 offset:17408
	ds_read_b128 v[206:209], v137 offset:16384
	ds_read_b128 v[210:213], v137 offset:17408
	global_load_lds_dwordx4 v[240:241], off
	v_lshl_add_u64 v[240:241], s[20:21], 0, v[132:133]
	v_readfirstlane_b32 s24, v152
	v_lshl_add_u64 v[242:243], v[240:241], 0, s[10:11]
	s_mov_b32 m0, s24
	s_add_u32 s20, s20, 0x100
	global_load_lds_dwordx4 v[242:243], off
	s_barrier
	s_waitcnt lgkmcnt(0)
	s_addc_u32 s21, s21, 0
	s_waitcnt lgkmcnt(0)
	v_mfma_f32_16x16x32_bf16 v[62:65], v[162:165], v[182:185], v[62:65]
	v_mfma_f32_16x16x32_bf16 v[58:61], v[174:177], v[182:185], v[58:61]
	v_mfma_f32_16x16x32_bf16 v[54:57], v[162:165], v[190:193], v[54:57]
	v_mfma_f32_16x16x32_bf16 v[50:53], v[174:177], v[190:193], v[50:53]
	v_mfma_f32_16x16x32_bf16 v[46:49], v[162:165], v[198:201], v[46:49]
	v_mfma_f32_16x16x32_bf16 v[42:45], v[174:177], v[198:201], v[42:45]
	v_mfma_f32_16x16x32_bf16 v[38:41], v[162:165], v[206:209], v[38:41]
	v_mfma_f32_16x16x32_bf16 v[34:37], v[174:177], v[206:209], v[34:37]
	v_mfma_f32_16x16x32_bf16 v[62:65], v[166:169], v[186:189], v[62:65]
	v_mfma_f32_16x16x32_bf16 v[58:61], v[178:181], v[186:189], v[58:61]
	v_mfma_f32_16x16x32_bf16 v[54:57], v[166:169], v[194:197], v[54:57]
	v_mfma_f32_16x16x32_bf16 v[50:53], v[178:181], v[194:197], v[50:53]
	v_mfma_f32_16x16x32_bf16 v[46:49], v[166:169], v[202:205], v[46:49]
	v_mfma_f32_16x16x32_bf16 v[42:45], v[178:181], v[202:205], v[42:45]
	v_mfma_f32_16x16x32_bf16 v[38:41], v[166:169], v[210:213], v[38:41]
	v_mfma_f32_16x16x32_bf16 v[34:37], v[178:181], v[210:213], v[34:37]
	s_barrier
; #define STAGE(P, GP, ktrel) do { const GAS char* _g = (GP) + (ktrel) * (BK * 2); \
;     __builtin_amdgcn_global_load_lds((const GAS unsigned*)(_g + so0), (unsigned*)((char*)(P) + tid_ * 16), 16, 0, 0); \
;     __builtin_amdgcn_global_load_lds((const GAS unsigned*)(_g + so1), (unsigned*)((char*)(P) + tid_ * 16 + 8192), 16, 0, 0); } while (0)
; #define WAIT_V(n) asm volatile("s_waitcnt vmcnt(" #n ")" ::: "memory")
; #define WAIT_L(n) asm volatile("s_waitcnt lgkmcnt(" #n ")" ::: "memory")
; #define BAR __builtin_amdgcn_s_barrier()
; #define SCHED __builtin_amdgcn_sched_barrier(0)
; #define LDA(dst, b, h) for (int m = 0; m < 4; ++m) for (int k = 0; k < 2; ++k) \
;     dst[m][k] = *reinterpret_cast<const bf16x8*>((char*)SA(b, h) + lds_byte(wr * 64 + m * 16 + fr, k * 32 + fq * 8))
; #define LDB(dst, b, h) for (int n = 0; n < 2; ++n) for (int k = 0; k < 2; ++k) \
;     dst[n][k] = *reinterpret_cast<const bf16x8*>((char*)SB(b, h) + lds_byte(wc * 32 + n * 16 + fr, k * 32 + fq * 8))
; #define MMA(ai, bj, At_, Bt_) do { __builtin_amdgcn_s_setprio(1); \
;     for (int m = 0; m < 4; ++m) for (int n = 0; n < 2; ++n) for (int k = 0; k < 2; ++k) \
;       acc[ai][bj][m][n] = __builtin_amdgcn_mfma_f32_16x16x32_bf16(At_[m][k], Bt_[n][k], acc[ai][bj][m][n], 0, 0, 0); \
;     __builtin_amdgcn_s_setprio(0); } while (0)
; template <int K, int LD = K>
; __device__ __forceinline__ void gemm_main(const GAS bf16* A, const GAS bf16* Bt, int brow, int bcol, f32x4 (&acc)[2][2][4][2]) {
;     ...
;     WAIT_V(6); BAR; MMA(1, 1, At, B1); BAR;
;     LDB(B0, 1, 0); SCHED; LDA(At, 1, 0); STAGE(SA(0, 1), pA1, 2);
;     WAIT_L(8); BAR; WAIT_L(0); MMA(0, 0, At, B0); BAR; SCHED;
;     LDB(B1, 1, 1); STAGE(SB(1, 0), pB0, 3);
;     BAR; WAIT_L(0); MMA(0, 1, At, B1); BAR;
;     LDA(At, 1, 1); STAGE(SA(1, 0), pA0, 3);
;     BAR; WAIT_L(0); MMA(1, 0, At, B0); BAR; SCHED;
;     STAGE(SB(1, 1), pB1, 3);
;     WAIT_V(6); BAR; MMA(1, 1, At, B1); BAR;
	v_lshl_add_u64 v[242:243], s[18:19], 0, v[130:131]
	v_readfirstlane_b32 s24, v147
	v_lshl_add_u64 v[162:163], v[242:243], 0, s[10:11]
	s_mov_b32 m0, s24
	v_lshl_add_u64 v[244:245], s[18:19], 0, v[132:133]
	v_readfirstlane_b32 s24, v158
	global_load_lds_dwordx4 v[162:163], off
	v_lshl_add_u64 v[162:163], v[244:245], 0, s[10:11]
	s_mov_b32 m0, s24
	s_add_u32 s18, s18, 0x100
	global_load_lds_dwordx4 v[162:163], off
	s_waitcnt vmcnt(10)
	s_addc_u32 s19, s19, 0
	s_barrier
	v_mfma_f32_16x16x32_bf16 v[30:33], v[214:217], v[182:185], v[30:33]
	v_mfma_f32_16x16x32_bf16 v[26:29], v[222:225], v[182:185], v[26:29]
	v_mfma_f32_16x16x32_bf16 v[22:25], v[214:217], v[190:193], v[22:25]
	v_mfma_f32_16x16x32_bf16 v[18:21], v[222:225], v[190:193], v[18:21]
	v_mfma_f32_16x16x32_bf16 v[14:17], v[214:217], v[198:201], v[14:17]
	v_mfma_f32_16x16x32_bf16 v[10:13], v[222:225], v[198:201], v[10:13]
	v_mfma_f32_16x16x32_bf16 v[6:9], v[214:217], v[206:209], v[6:9]
	v_mfma_f32_16x16x32_bf16 v[2:5], v[222:225], v[206:209], v[2:5]
	v_mfma_f32_16x16x32_bf16 v[30:33], v[218:221], v[186:189], v[30:33]
	v_mfma_f32_16x16x32_bf16 v[26:29], v[226:229], v[186:189], v[26:29]
	v_mfma_f32_16x16x32_bf16 v[22:25], v[218:221], v[194:197], v[22:25]
	v_mfma_f32_16x16x32_bf16 v[18:21], v[226:229], v[194:197], v[18:21]
	v_mfma_f32_16x16x32_bf16 v[14:17], v[218:221], v[202:205], v[14:17]
	v_mfma_f32_16x16x32_bf16 v[10:13], v[226:229], v[202:205], v[10:13]
	v_mfma_f32_16x16x32_bf16 v[6:9], v[218:221], v[210:213], v[6:9]
	v_mfma_f32_16x16x32_bf16 v[2:5], v[226:229], v[210:213], v[2:5]
	s_barrier
	ds_read_b128 v[162:165], v142
	ds_read_b128 v[166:169], v142 offset:1024
	ds_read_b128 v[174:177], v142 offset:2048
	ds_read_b128 v[178:181], v142 offset:3072
	v_readfirstlane_b32 s24, v153
	v_lshl_add_u64 v[214:215], v[230:231], 0, s[10:11]
	s_mov_b32 m0, s24
	v_readfirstlane_b32 s24, v154
	ds_read_b128 v[182:185], v140 offset:32768
	ds_read_b128 v[186:189], v140 offset:33792
	ds_read_b128 v[190:193], v139 offset:32768
	ds_read_b128 v[194:197], v139 offset:33792
	ds_read_b128 v[198:201], v138 offset:32768
	ds_read_b128 v[202:205], v138 offset:33792
	ds_read_b128 v[206:209], v137 offset:32768
	ds_read_b128 v[210:213], v137 offset:33792
	global_load_lds_dwordx4 v[214:215], off
	v_lshl_add_u64 v[214:215], v[232:233], 0, s[10:11]
	s_mov_b32 m0, s24
	s_add_u32 s14, s14, 0x100
	global_load_lds_dwordx4 v[214:215], off
	s_waitcnt lgkmcnt(8)
	s_waitcnt vmcnt(10)
	s_barrier
	s_waitcnt lgkmcnt(0)
	s_addc_u32 s15, s15, 0
	s_waitcnt lgkmcnt(0)
	v_mfma_f32_16x16x32_bf16 v[126:129], v[162:165], v[182:185], v[126:129]
	v_mfma_f32_16x16x32_bf16 v[122:125], v[174:177], v[182:185], v[122:125]
	v_mfma_f32_16x16x32_bf16 v[118:121], v[162:165], v[190:193], v[118:121]
	v_mfma_f32_16x16x32_bf16 v[114:117], v[174:177], v[190:193], v[114:117]
	v_mfma_f32_16x16x32_bf16 v[110:113], v[162:165], v[198:201], v[110:113]
	v_mfma_f32_16x16x32_bf16 v[106:109], v[174:177], v[198:201], v[106:109]
	v_mfma_f32_16x16x32_bf16 v[102:105], v[162:165], v[206:209], v[102:105]
	v_mfma_f32_16x16x32_bf16 v[98:101], v[174:177], v[206:209], v[98:101]
	v_mfma_f32_16x16x32_bf16 v[126:129], v[166:169], v[186:189], v[126:129]
	v_mfma_f32_16x16x32_bf16 v[122:125], v[178:181], v[186:189], v[122:125]
	v_mfma_f32_16x16x32_bf16 v[118:121], v[166:169], v[194:197], v[118:121]
	v_mfma_f32_16x16x32_bf16 v[114:117], v[178:181], v[194:197], v[114:117]
	v_mfma_f32_16x16x32_bf16 v[110:113], v[166:169], v[202:205], v[110:113]
	v_mfma_f32_16x16x32_bf16 v[106:109], v[178:181], v[202:205], v[106:109]
	v_mfma_f32_16x16x32_bf16 v[102:105], v[166:169], v[210:213], v[102:105]
	v_mfma_f32_16x16x32_bf16 v[98:101], v[178:181], v[210:213], v[98:101]
	s_barrier
	v_readfirstlane_b32 s24, v148
	v_lshl_add_u64 v[230:231], v[234:235], 0, s[12:13]
	s_mov_b32 m0, s24
	v_readfirstlane_b32 s24, v159
	ds_read_b128 v[214:217], v141
	ds_read_b128 v[218:221], v141 offset:1024
	ds_read_b128 v[222:225], v141 offset:2048
	ds_read_b128 v[226:229], v141 offset:3072
	global_load_lds_dwordx4 v[230:231], off
	v_lshl_add_u64 v[230:231], v[236:237], 0, s[12:13]
	s_mov_b32 m0, s24
	s_nop 0
	global_load_lds_dwordx4 v[230:231], off
	s_waitcnt vmcnt(10)
	s_barrier
	s_waitcnt lgkmcnt(0)
	s_waitcnt lgkmcnt(0)
	v_mfma_f32_16x16x32_bf16 v[94:97], v[214:217], v[182:185], v[94:97]
	v_mfma_f32_16x16x32_bf16 v[90:93], v[222:225], v[182:185], v[90:93]
	v_mfma_f32_16x16x32_bf16 v[86:89], v[214:217], v[190:193], v[86:89]
	v_mfma_f32_16x16x32_bf16 v[82:85], v[222:225], v[190:193], v[82:85]
	v_mfma_f32_16x16x32_bf16 v[78:81], v[214:217], v[198:201], v[78:81]
	v_mfma_f32_16x16x32_bf16 v[74:77], v[222:225], v[198:201], v[74:77]
	v_mfma_f32_16x16x32_bf16 v[70:73], v[214:217], v[206:209], v[70:73]
	v_mfma_f32_16x16x32_bf16 v[66:69], v[222:225], v[206:209], v[66:69]
	v_mfma_f32_16x16x32_bf16 v[94:97], v[218:221], v[186:189], v[94:97]
	v_mfma_f32_16x16x32_bf16 v[90:93], v[226:229], v[186:189], v[90:93]
	v_mfma_f32_16x16x32_bf16 v[86:89], v[218:221], v[194:197], v[86:89]
	v_mfma_f32_16x16x32_bf16 v[82:85], v[226:229], v[194:197], v[82:85]
	v_mfma_f32_16x16x32_bf16 v[78:81], v[218:221], v[202:205], v[78:81]
	v_mfma_f32_16x16x32_bf16 v[74:77], v[226:229], v[202:205], v[74:77]
	v_mfma_f32_16x16x32_bf16 v[70:73], v[218:221], v[210:213], v[70:73]
	v_mfma_f32_16x16x32_bf16 v[66:69], v[226:229], v[210:213], v[66:69]
	v_readfirstlane_b32 s24, v155
	v_lshl_add_u64 v[230:231], v[238:239], 0, s[12:13]
	s_mov_b32 m0, s24
	v_readfirstlane_b32 s24, v156
	s_barrier
; #define STAGE(P, GP, ktrel) do { const GAS char* _g = (GP) + (ktrel) * (BK * 2); \
;     __builtin_amdgcn_global_load_lds((const GAS unsigned*)(_g + so0), (unsigned*)((char*)(P) + tid_ * 16), 16, 0, 0); \
;     __builtin_amdgcn_global_load_lds((const GAS unsigned*)(_g + so1), (unsigned*)((char*)(P) + tid_ * 16 + 8192), 16, 0, 0); } while (0)
; #define WAIT_V(n) asm volatile("s_waitcnt vmcnt(" #n ")" ::: "memory")
; #define WAIT_L(n) asm volatile("s_waitcnt lgkmcnt(" #n ")" ::: "memory")
; #define BAR __builtin_amdgcn_s_barrier()
; #define SCHED __builtin_amdgcn_sched_barrier(0)
; #define LDA(dst, b, h) for (int m = 0; m < 4; ++m) for (int k = 0; k < 2; ++k) \
;     dst[m][k] = *reinterpret_cast<const bf16x8*>((char*)SA(b, h) + lds_byte(wr * 64 + m * 16 + fr, k * 32 + fq * 8))
; #define LDB(dst, b, h) for (int n = 0; n < 2; ++n) for (int k = 0; k < 2; ++k) \
;     dst[n][k] = *reinterpret_cast<const bf16x8*>((char*)SB(b, h) + lds_byte(wc * 32 + n * 16 + fr, k * 32 + fq * 8))
; #define MMA(ai, bj, At_, Bt_) do { __builtin_amdgcn_s_setprio(1); \
;     for (int m = 0; m < 4; ++m) for (int n = 0; n < 2; ++n) for (int k = 0; k < 2; ++k) \
;       acc[ai][bj][m][n] = __builtin_amdgcn_mfma_f32_16x16x32_bf16(At_[m][k], Bt_[n][k], acc[ai][bj][m][n], 0, 0, 0); \
;     __builtin_amdgcn_s_setprio(0); } while (0)
; template <int K, int LD = K>
; __device__ __forceinline__ void gemm_main(const GAS bf16* A, const GAS bf16* Bt, int brow, int bcol, f32x4 (&acc)[2][2][4][2]) {
;     ...
;     LDA(At, 1, 1); STAGE(SA(1, 0), pA0, 3);
;     BAR; WAIT_L(0); MMA(1, 0, At, B0); BAR; SCHED;
;     STAGE(SB(1, 1), pB1, 3);
;     WAIT_V(6); BAR; MMA(1, 1, At, B1); BAR;
;     pA0 += 4 * BK; pA1 += 4 * BK; pB0 += 4 * BK; pB1 += 4 * BK;
;     asm volatile("" : "+s"(pA0), "+s"(pA1), "+s"(pB0), "+s"(pB1));
;   }
;   { LDB(B0, 0, 0); LDA(At, 0, 0); STAGE(SA(1, 1), pA1, 1);
;     BAR; WAIT_L(0); MMA(0, 0, At, B0); BAR;
;     LDB(B1, 0, 1); BAR; WAIT_L(0); MMA(0, 1, At, B1); BAR;
	ds_read_b128 v[182:185], v140 offset:49152
	ds_read_b128 v[186:189], v140 offset:50176
	ds_read_b128 v[190:193], v139 offset:49152
	ds_read_b128 v[194:197], v139 offset:50176
	ds_read_b128 v[198:201], v138 offset:49152
	ds_read_b128 v[202:205], v138 offset:50176
	ds_read_b128 v[206:209], v137 offset:49152
	ds_read_b128 v[210:213], v137 offset:50176
	global_load_lds_dwordx4 v[230:231], off
	v_lshl_add_u64 v[230:231], v[240:241], 0, s[12:13]
	s_mov_b32 m0, s24
	s_nop 0
	global_load_lds_dwordx4 v[230:231], off
	s_barrier
	s_waitcnt lgkmcnt(0)
	s_waitcnt lgkmcnt(0)
	v_mfma_f32_16x16x32_bf16 v[62:65], v[162:165], v[182:185], v[62:65]
	v_mfma_f32_16x16x32_bf16 v[58:61], v[174:177], v[182:185], v[58:61]
	v_mfma_f32_16x16x32_bf16 v[54:57], v[162:165], v[190:193], v[54:57]
	v_mfma_f32_16x16x32_bf16 v[50:53], v[174:177], v[190:193], v[50:53]
	v_mfma_f32_16x16x32_bf16 v[46:49], v[162:165], v[198:201], v[46:49]
	v_mfma_f32_16x16x32_bf16 v[42:45], v[174:177], v[198:201], v[42:45]
	v_mfma_f32_16x16x32_bf16 v[38:41], v[162:165], v[206:209], v[38:41]
	v_mfma_f32_16x16x32_bf16 v[34:37], v[174:177], v[206:209], v[34:37]
	v_mfma_f32_16x16x32_bf16 v[62:65], v[166:169], v[186:189], v[62:65]
	v_mfma_f32_16x16x32_bf16 v[58:61], v[178:181], v[186:189], v[58:61]
	v_mfma_f32_16x16x32_bf16 v[54:57], v[166:169], v[194:197], v[54:57]
	v_mfma_f32_16x16x32_bf16 v[50:53], v[178:181], v[194:197], v[50:53]
	v_mfma_f32_16x16x32_bf16 v[46:49], v[166:169], v[202:205], v[46:49]
	v_mfma_f32_16x16x32_bf16 v[42:45], v[178:181], v[202:205], v[42:45]
	v_mfma_f32_16x16x32_bf16 v[38:41], v[166:169], v[210:213], v[38:41]
	v_mfma_f32_16x16x32_bf16 v[34:37], v[178:181], v[210:213], v[34:37]
	s_barrier
	v_readfirstlane_b32 s24, v149
	v_lshl_add_u64 v[162:163], v[242:243], 0, s[12:13]
	s_mov_b32 m0, s24
	v_readfirstlane_b32 s24, v160
	global_load_lds_dwordx4 v[162:163], off
	v_lshl_add_u64 v[162:163], v[244:245], 0, s[12:13]
	s_mov_b32 m0, s24
	s_nop 0
	global_load_lds_dwordx4 v[162:163], off
	s_waitcnt vmcnt(10)
	s_barrier
	v_mfma_f32_16x16x32_bf16 v[30:33], v[214:217], v[182:185], v[30:33]
	v_mfma_f32_16x16x32_bf16 v[26:29], v[222:225], v[182:185], v[26:29]
	v_mfma_f32_16x16x32_bf16 v[22:25], v[214:217], v[190:193], v[22:25]
	v_mfma_f32_16x16x32_bf16 v[18:21], v[222:225], v[190:193], v[18:21]
	v_mfma_f32_16x16x32_bf16 v[14:17], v[214:217], v[198:201], v[14:17]
	v_mfma_f32_16x16x32_bf16 v[10:13], v[222:225], v[198:201], v[10:13]
	v_mfma_f32_16x16x32_bf16 v[6:9], v[214:217], v[206:209], v[6:9]
	v_mfma_f32_16x16x32_bf16 v[2:5], v[222:225], v[206:209], v[2:5]
	v_mfma_f32_16x16x32_bf16 v[30:33], v[218:221], v[186:189], v[30:33]
	v_mfma_f32_16x16x32_bf16 v[26:29], v[226:229], v[186:189], v[26:29]
	v_mfma_f32_16x16x32_bf16 v[22:25], v[218:221], v[194:197], v[22:25]
	v_mfma_f32_16x16x32_bf16 v[18:21], v[226:229], v[194:197], v[18:21]
	v_mfma_f32_16x16x32_bf16 v[14:17], v[218:221], v[202:205], v[14:17]
	v_mfma_f32_16x16x32_bf16 v[10:13], v[226:229], v[202:205], v[10:13]
	v_mfma_f32_16x16x32_bf16 v[6:9], v[218:221], v[210:213], v[6:9]
	v_mfma_f32_16x16x32_bf16 v[2:5], v[226:229], v[210:213], v[2:5]
	s_add_i32 s17, s17, 2
	s_cmp_lt_u32 s17, 12
	s_barrier
	s_cbranch_scc1 .LBB0_89
	ds_read_b128 v[146:149], v144
	ds_read_b128 v[152:155], v144 offset:1024
	ds_read_b128 v[156:159], v144 offset:2048
	ds_read_b128 v[160:163], v144 offset:3072
	ds_read_b128 v[164:167], v140
	ds_read_b128 v[174:177], v140 offset:1024
	ds_read_b128 v[178:181], v139
	ds_read_b128 v[182:185], v139 offset:1024
	ds_read_b128 v[186:189], v138
	ds_read_b128 v[190:193], v138 offset:1024
	ds_read_b128 v[194:197], v137
	ds_read_b128 v[198:201], v137 offset:1024
	v_lshl_add_u64 v[144:145], s[14:15], 0, v[130:131]
	v_readfirstlane_b32 s17, v151
	v_lshl_add_u64 v[144:145], v[144:145], 0, s[8:9]
	s_mov_b32 m0, s17
	v_lshl_add_u64 v[132:133], s[14:15], 0, v[132:133]
	v_readfirstlane_b32 s14, v150
	global_load_lds_dwordx4 v[144:145], off
	v_lshl_add_u64 v[132:133], v[132:133], 0, s[8:9]
	s_mov_b32 m0, s14
	s_nop 0
	global_load_lds_dwordx4 v[132:133], off
	s_waitcnt vmcnt(10)
	s_barrier
	s_waitcnt lgkmcnt(0)
	s_waitcnt lgkmcnt(0)
	v_mfma_f32_16x16x32_bf16 v[126:129], v[146:149], v[164:167], v[126:129]
	v_mfma_f32_16x16x32_bf16 v[122:125], v[156:159], v[164:167], v[122:125]
	v_mfma_f32_16x16x32_bf16 v[110:113], v[146:149], v[186:189], v[110:113]
	v_mfma_f32_16x16x32_bf16 v[106:109], v[156:159], v[186:189], v[106:109]
	v_mfma_f32_16x16x32_bf16 v[126:129], v[152:155], v[174:177], v[126:129]
	v_mfma_f32_16x16x32_bf16 v[122:125], v[160:163], v[174:177], v[122:125]
	v_mfma_f32_16x16x32_bf16 v[118:121], v[146:149], v[178:181], v[118:121]
	v_mfma_f32_16x16x32_bf16 v[114:117], v[156:159], v[178:181], v[114:117]
	v_mfma_f32_16x16x32_bf16 v[110:113], v[152:155], v[190:193], v[110:113]
	v_mfma_f32_16x16x32_bf16 v[106:109], v[160:163], v[190:193], v[106:109]
	v_mfma_f32_16x16x32_bf16 v[102:105], v[146:149], v[194:197], v[102:105]
	v_mfma_f32_16x16x32_bf16 v[98:101], v[156:159], v[194:197], v[98:101]
	v_mfma_f32_16x16x32_bf16 v[202:205], v[152:155], v[182:185], v[118:121]
	v_mfma_f32_16x16x32_bf16 v[206:209], v[160:163], v[182:185], v[114:117]
	v_mfma_f32_16x16x32_bf16 v[210:213], v[152:155], v[198:201], v[102:105]
	v_mfma_f32_16x16x32_bf16 v[214:217], v[160:163], v[198:201], v[98:101]
	s_barrier
	s_nop 1
	ds_read_b128 v[98:101], v143
	ds_read_b128 v[102:105], v143 offset:1024
	ds_read_b128 v[114:117], v143 offset:2048
	ds_read_b128 v[118:121], v143 offset:3072
	s_waitcnt vmcnt(8)
	s_barrier
; #define WAIT_V(n) asm volatile("s_waitcnt vmcnt(" #n ")" ::: "memory")
; #define WAIT_L(n) asm volatile("s_waitcnt lgkmcnt(" #n ")" ::: "memory")
; #define BAR __builtin_amdgcn_s_barrier()
; #define LDA(dst, b, h) for (int m = 0; m < 4; ++m) for (int k = 0; k < 2; ++k) \
;     dst[m][k] = *reinterpret_cast<const bf16x8*>((char*)SA(b, h) + lds_byte(wr * 64 + m * 16 + fr, k * 32 + fq * 8))
; #define LDB(dst, b, h) for (int n = 0; n < 2; ++n) for (int k = 0; k < 2; ++k) \
;     dst[n][k] = *reinterpret_cast<const bf16x8*>((char*)SB(b, h) + lds_byte(wc * 32 + n * 16 + fr, k * 32 + fq * 8))
; #define MMA(ai, bj, At_, Bt_) do { __builtin_amdgcn_s_setprio(1); \
;     for (int m = 0; m < 4; ++m) for (int n = 0; n < 2; ++n) for (int k = 0; k < 2; ++k) \
;       acc[ai][bj][m][n] = __builtin_amdgcn_mfma_f32_16x16x32_bf16(At_[m][k], Bt_[n][k], acc[ai][bj][m][n], 0, 0, 0); \
;     __builtin_amdgcn_s_setprio(0); } while (0)
; template <int K, int LD = K>
; __device__ __forceinline__ void gemm_main(const GAS bf16* A, const GAS bf16* Bt, int brow, int bcol, f32x4 (&acc)[2][2][4][2]) {
;     ...
;     LDB(B1, 0, 1); BAR; WAIT_L(0); MMA(0, 1, At, B1); BAR;
;     LDA(At, 0, 1); WAIT_V(4); BAR; WAIT_L(0); MMA(1, 0, At, B0); MMA(1, 1, At, B1); BAR; }
;   { LDB(B0, 1, 0); LDA(At, 1, 0); WAIT_V(2); BAR; WAIT_L(0); MMA(0, 0, At, B0); BAR;
;     LDB(B1, 1, 1); WAIT_V(0); BAR; WAIT_L(0); MMA(0, 1, At, B1); BAR;
	s_waitcnt lgkmcnt(0)
	s_waitcnt lgkmcnt(0)
	v_mfma_f32_16x16x32_bf16 v[94:97], v[98:101], v[164:167], v[94:97]
	v_mfma_f32_16x16x32_bf16 v[90:93], v[114:117], v[164:167], v[90:93]
	v_mfma_f32_16x16x32_bf16 v[78:81], v[98:101], v[186:189], v[78:81]
	v_mfma_f32_16x16x32_bf16 v[74:77], v[114:117], v[186:189], v[74:77]
	v_mfma_f32_16x16x32_bf16 v[94:97], v[102:105], v[174:177], v[94:97]
	v_mfma_f32_16x16x32_bf16 v[90:93], v[118:121], v[174:177], v[90:93]
	v_mfma_f32_16x16x32_bf16 v[86:89], v[98:101], v[178:181], v[86:89]
	v_mfma_f32_16x16x32_bf16 v[82:85], v[114:117], v[178:181], v[82:85]
	v_mfma_f32_16x16x32_bf16 v[78:81], v[102:105], v[190:193], v[78:81]
	v_mfma_f32_16x16x32_bf16 v[74:77], v[118:121], v[190:193], v[74:77]
	v_mfma_f32_16x16x32_bf16 v[70:73], v[98:101], v[194:197], v[70:73]
	v_mfma_f32_16x16x32_bf16 v[66:69], v[114:117], v[194:197], v[66:69]
	v_mfma_f32_16x16x32_bf16 v[164:167], v[102:105], v[182:185], v[86:89]
	v_mfma_f32_16x16x32_bf16 v[174:177], v[118:121], v[182:185], v[82:85]
	v_mfma_f32_16x16x32_bf16 v[178:181], v[102:105], v[198:201], v[70:73]
	v_mfma_f32_16x16x32_bf16 v[182:185], v[118:121], v[198:201], v[66:69]
	s_barrier
	s_nop 1
	ds_read_b128 v[66:69], v140 offset:16384
	ds_read_b128 v[70:73], v140 offset:17408
	ds_read_b128 v[82:85], v139 offset:16384
	ds_read_b128 v[86:89], v139 offset:17408
	ds_read_b128 v[186:189], v138 offset:16384
	ds_read_b128 v[190:193], v138 offset:17408
	ds_read_b128 v[194:197], v137 offset:16384
	ds_read_b128 v[198:201], v137 offset:17408
	s_waitcnt vmcnt(4)
	s_barrier
	s_waitcnt lgkmcnt(0)
	s_waitcnt lgkmcnt(0)
	v_mfma_f32_16x16x32_bf16 v[62:65], v[146:149], v[66:69], v[62:65]
	v_mfma_f32_16x16x32_bf16 v[58:61], v[156:159], v[66:69], v[58:61]
	v_mfma_f32_16x16x32_bf16 v[46:49], v[146:149], v[186:189], v[46:49]
	v_mfma_f32_16x16x32_bf16 v[38:41], v[146:149], v[194:197], v[38:41]
	v_mfma_f32_16x16x32_bf16 v[62:65], v[152:155], v[70:73], v[62:65]
	v_mfma_f32_16x16x32_bf16 v[58:61], v[160:163], v[70:73], v[58:61]
	v_mfma_f32_16x16x32_bf16 v[54:57], v[146:149], v[82:85], v[54:57]
	v_mfma_f32_16x16x32_bf16 v[50:53], v[156:159], v[82:85], v[50:53]
	v_mfma_f32_16x16x32_bf16 v[46:49], v[152:155], v[190:193], v[46:49]
	v_mfma_f32_16x16x32_bf16 v[42:45], v[156:159], v[186:189], v[42:45]
	v_mfma_f32_16x16x32_bf16 v[38:41], v[152:155], v[198:201], v[38:41]
	v_mfma_f32_16x16x32_bf16 v[34:37], v[156:159], v[194:197], v[34:37]
	v_mfma_f32_16x16x32_bf16 v[218:221], v[152:155], v[86:89], v[54:57]
	v_mfma_f32_16x16x32_bf16 v[222:225], v[160:163], v[86:89], v[50:53]
	v_mfma_f32_16x16x32_bf16 v[226:229], v[160:163], v[190:193], v[42:45]
	v_mfma_f32_16x16x32_bf16 v[144:147], v[160:163], v[198:201], v[34:37]
	v_mfma_f32_16x16x32_bf16 v[30:33], v[98:101], v[66:69], v[30:33]
	v_mfma_f32_16x16x32_bf16 v[26:29], v[114:117], v[66:69], v[26:29]
	v_mfma_f32_16x16x32_bf16 v[14:17], v[98:101], v[186:189], v[14:17]
	v_mfma_f32_16x16x32_bf16 v[6:9], v[98:101], v[194:197], v[6:9]
	v_mfma_f32_16x16x32_bf16 v[30:33], v[102:105], v[70:73], v[30:33]
	v_mfma_f32_16x16x32_bf16 v[26:29], v[118:121], v[70:73], v[26:29]
	v_mfma_f32_16x16x32_bf16 v[22:25], v[98:101], v[82:85], v[22:25]
	v_mfma_f32_16x16x32_bf16 v[18:21], v[114:117], v[82:85], v[18:21]
	v_mfma_f32_16x16x32_bf16 v[14:17], v[102:105], v[190:193], v[14:17]
	v_mfma_f32_16x16x32_bf16 v[10:13], v[114:117], v[186:189], v[10:13]
	v_mfma_f32_16x16x32_bf16 v[6:9], v[102:105], v[198:201], v[6:9]
	v_mfma_f32_16x16x32_bf16 v[2:5], v[114:117], v[194:197], v[2:5]
	v_mfma_f32_16x16x32_bf16 v[148:151], v[102:105], v[86:89], v[22:25]
	v_mfma_f32_16x16x32_bf16 v[152:155], v[118:121], v[86:89], v[18:21]
	v_mfma_f32_16x16x32_bf16 v[156:159], v[118:121], v[190:193], v[10:13]
	v_mfma_f32_16x16x32_bf16 v[160:163], v[118:121], v[198:201], v[2:5]
	s_barrier
	s_nop 1
	ds_read_b128 v[2:5], v142
	ds_read_b128 v[10:13], v142 offset:1024
	ds_read_b128 v[186:189], v142 offset:2048
	ds_read_b128 v[190:193], v142 offset:3072
	ds_read_b128 v[18:21], v140 offset:32768
	ds_read_b128 v[22:25], v140 offset:33792
	ds_read_b128 v[34:37], v139 offset:32768
	ds_read_b128 v[42:45], v139 offset:33792
	ds_read_b128 v[50:53], v138 offset:32768
	ds_read_b128 v[54:57], v138 offset:33792
	ds_read_b128 v[194:197], v137 offset:32768
	ds_read_b128 v[198:201], v137 offset:33792
	s_waitcnt vmcnt(2)
	s_barrier
	s_waitcnt lgkmcnt(0)
	s_waitcnt lgkmcnt(0)
	v_mfma_f32_16x16x32_bf16 v[66:69], v[2:5], v[18:21], v[126:129]
	v_mfma_f32_16x16x32_bf16 v[118:121], v[10:13], v[22:25], v[66:69]
	v_mfma_f32_16x16x32_bf16 v[66:69], v[186:189], v[18:21], v[122:125]
	v_mfma_f32_16x16x32_bf16 v[114:117], v[190:193], v[22:25], v[66:69]
	v_mfma_f32_16x16x32_bf16 v[66:69], v[2:5], v[34:37], v[202:205]
	v_mfma_f32_16x16x32_bf16 v[102:105], v[10:13], v[42:45], v[66:69]
	v_mfma_f32_16x16x32_bf16 v[66:69], v[186:189], v[34:37], v[206:209]
	v_mfma_f32_16x16x32_bf16 v[98:101], v[190:193], v[42:45], v[66:69]
	v_mfma_f32_16x16x32_bf16 v[66:69], v[2:5], v[50:53], v[110:113]
	v_mfma_f32_16x16x32_bf16 v[86:89], v[10:13], v[54:57], v[66:69]
	v_mfma_f32_16x16x32_bf16 v[66:69], v[186:189], v[50:53], v[106:109]
	v_mfma_f32_16x16x32_bf16 v[82:85], v[190:193], v[54:57], v[66:69]
	v_mfma_f32_16x16x32_bf16 v[66:69], v[2:5], v[194:197], v[210:213]
	v_mfma_f32_16x16x32_bf16 v[70:73], v[10:13], v[198:201], v[66:69]
	v_mfma_f32_16x16x32_bf16 v[66:69], v[186:189], v[194:197], v[214:217]
	v_mfma_f32_16x16x32_bf16 v[66:69], v[190:193], v[198:201], v[66:69]
	s_barrier
	ds_read_b128 v[202:205], v141
	ds_read_b128 v[206:209], v141 offset:1024
	ds_read_b128 v[210:213], v141 offset:2048
	ds_read_b128 v[214:217], v141 offset:3072
	s_waitcnt vmcnt(0)
	s_barrier
; #define WAIT_V(n) asm volatile("s_waitcnt vmcnt(" #n ")" ::: "memory")
; #define WAIT_L(n) asm volatile("s_waitcnt lgkmcnt(" #n ")" ::: "memory")
; #define BAR __builtin_amdgcn_s_barrier()
; #define LDA(dst, b, h) for (int m = 0; m < 4; ++m) for (int k = 0; k < 2; ++k) \
;     dst[m][k] = *reinterpret_cast<const bf16x8*>((char*)SA(b, h) + lds_byte(wr * 64 + m * 16 + fr, k * 32 + fq * 8))
; #define LDB(dst, b, h) for (int n = 0; n < 2; ++n) for (int k = 0; k < 2; ++k) \
;     dst[n][k] = *reinterpret_cast<const bf16x8*>((char*)SB(b, h) + lds_byte(wc * 32 + n * 16 + fr, k * 32 + fq * 8))
; #define MMA(ai, bj, At_, Bt_) do { __builtin_amdgcn_s_setprio(1); \
;     for (int m = 0; m < 4; ++m) for (int n = 0; n < 2; ++n) for (int k = 0; k < 2; ++k) \
;       acc[ai][bj][m][n] = __builtin_amdgcn_mfma_f32_16x16x32_bf16(At_[m][k], Bt_[n][k], acc[ai][bj][m][n], 0, 0, 0); \
;     __builtin_amdgcn_s_setprio(0); } while (0)
; template <int K, int LD = K>
; __device__ __forceinline__ void gemm_main(const GAS bf16* A, const GAS bf16* Bt, int brow, int bcol, f32x4 (&acc)[2][2][4][2]) {
;     ...
;     LDB(B1, 1, 1); WAIT_V(0); BAR; WAIT_L(0); MMA(0, 1, At, B1); BAR;
;     LDA(At, 1, 1); BAR; WAIT_L(0); MMA(1, 0, At, B0); MMA(1, 1, At, B1); BAR; }
;   if (wr == 0) BAR;
	s_waitcnt lgkmcnt(0)
	s_waitcnt lgkmcnt(0)
	v_mfma_f32_16x16x32_bf16 v[94:97], v[202:205], v[18:21], v[94:97]
	v_mfma_f32_16x16x32_bf16 v[18:21], v[210:213], v[18:21], v[90:93]
	v_mfma_f32_16x16x32_bf16 v[122:125], v[214:217], v[22:25], v[18:21]
	v_mfma_f32_16x16x32_bf16 v[18:21], v[202:205], v[34:37], v[164:167]
	v_mfma_f32_16x16x32_bf16 v[110:113], v[206:209], v[42:45], v[18:21]
	v_mfma_f32_16x16x32_bf16 v[18:21], v[210:213], v[34:37], v[174:177]
	v_mfma_f32_16x16x32_bf16 v[106:109], v[214:217], v[42:45], v[18:21]
	v_mfma_f32_16x16x32_bf16 v[18:21], v[202:205], v[50:53], v[78:81]
	v_mfma_f32_16x16x32_bf16 v[126:129], v[206:209], v[22:25], v[94:97]
	v_mfma_f32_16x16x32_bf16 v[94:97], v[206:209], v[54:57], v[18:21]
	v_mfma_f32_16x16x32_bf16 v[18:21], v[210:213], v[50:53], v[74:77]
	v_mfma_f32_16x16x32_bf16 v[90:93], v[214:217], v[54:57], v[18:21]
	v_mfma_f32_16x16x32_bf16 v[18:21], v[202:205], v[194:197], v[178:181]
	v_mfma_f32_16x16x32_bf16 v[78:81], v[206:209], v[198:201], v[18:21]
	v_mfma_f32_16x16x32_bf16 v[18:21], v[210:213], v[194:197], v[182:185]
	v_mfma_f32_16x16x32_bf16 v[74:77], v[214:217], v[198:201], v[18:21]
	s_barrier
	ds_read_b128 v[164:167], v140 offset:49152
	ds_read_b128 v[140:143], v140 offset:50176
	ds_read_b128 v[174:177], v139 offset:49152
	ds_read_b128 v[178:181], v139 offset:50176
	ds_read_b128 v[182:185], v138 offset:49152
	ds_read_b128 v[194:197], v138 offset:50176
	ds_read_b128 v[198:201], v137 offset:49152
	ds_read_b128 v[230:233], v137 offset:50176
	s_barrier
	s_waitcnt lgkmcnt(0)
	s_waitcnt lgkmcnt(0)
	v_mfma_f32_16x16x32_bf16 v[18:21], v[2:5], v[164:167], v[62:65]
	v_mfma_f32_16x16x32_bf16 v[54:57], v[10:13], v[140:143], v[18:21]
	v_mfma_f32_16x16x32_bf16 v[18:21], v[186:189], v[164:167], v[58:61]
	v_mfma_f32_16x16x32_bf16 v[50:53], v[190:193], v[140:143], v[18:21]
	v_mfma_f32_16x16x32_bf16 v[18:21], v[2:5], v[174:177], v[218:221]
	v_mfma_f32_16x16x32_bf16 v[42:45], v[10:13], v[178:181], v[18:21]
	v_mfma_f32_16x16x32_bf16 v[18:21], v[186:189], v[174:177], v[222:225]
	v_mfma_f32_16x16x32_bf16 v[34:37], v[190:193], v[178:181], v[18:21]
	v_mfma_f32_16x16x32_bf16 v[18:21], v[2:5], v[182:185], v[46:49]
	v_mfma_f32_16x16x32_bf16 v[2:5], v[2:5], v[198:201], v[38:41]
	v_mfma_f32_16x16x32_bf16 v[22:25], v[10:13], v[194:197], v[18:21]
	v_mfma_f32_16x16x32_bf16 v[18:21], v[186:189], v[182:185], v[226:229]
	v_mfma_f32_16x16x32_bf16 v[10:13], v[10:13], v[230:233], v[2:5]
	v_mfma_f32_16x16x32_bf16 v[2:5], v[186:189], v[198:201], v[144:147]
	v_mfma_f32_16x16x32_bf16 v[18:21], v[190:193], v[194:197], v[18:21]
	v_mfma_f32_16x16x32_bf16 v[2:5], v[190:193], v[230:233], v[2:5]
	v_mfma_f32_16x16x32_bf16 v[26:29], v[210:213], v[164:167], v[26:29]
	v_mfma_f32_16x16x32_bf16 v[30:33], v[202:205], v[164:167], v[30:33]
	v_mfma_f32_16x16x32_bf16 v[58:61], v[214:217], v[140:143], v[26:29]
	v_mfma_f32_16x16x32_bf16 v[26:29], v[202:205], v[174:177], v[148:151]
	v_mfma_f32_16x16x32_bf16 v[14:17], v[202:205], v[182:185], v[14:17]
	v_mfma_f32_16x16x32_bf16 v[62:65], v[206:209], v[140:143], v[30:33]
	v_mfma_f32_16x16x32_bf16 v[46:49], v[206:209], v[178:181], v[26:29]
	v_mfma_f32_16x16x32_bf16 v[26:29], v[210:213], v[174:177], v[152:155]
	v_mfma_f32_16x16x32_bf16 v[30:33], v[206:209], v[194:197], v[14:17]
	v_mfma_f32_16x16x32_bf16 v[14:17], v[210:213], v[182:185], v[156:159]
	v_mfma_f32_16x16x32_bf16 v[6:9], v[202:205], v[198:201], v[6:9]
	v_mfma_f32_16x16x32_bf16 v[38:41], v[214:217], v[178:181], v[26:29]
	v_mfma_f32_16x16x32_bf16 v[26:29], v[214:217], v[194:197], v[14:17]
	v_mfma_f32_16x16x32_bf16 v[14:17], v[206:209], v[230:233], v[6:9]
	v_mfma_f32_16x16x32_bf16 v[6:9], v[210:213], v[198:201], v[160:163]
	v_mfma_f32_16x16x32_bf16 v[6:9], v[214:217], v[230:233], v[6:9]
	v_cmp_gt_u32_e32 vcc, s34, v136
	s_barrier
	s_and_saveexec_b64 s[14:15], vcc
	s_cbranch_execz .LBB0_92
	s_barrier
; #define GAS __attribute__((address_space(1)))
; __device__ __forceinline__ int otid() { int t = threadIdx.x; asm volatile("" : "+v"(t)); return t; }
; #define STAGE(P, GP, ktrel) do { const GAS char* _g = (GP) + (ktrel) * (BK * 2); \
;     __builtin_amdgcn_global_load_lds((const GAS unsigned*)(_g + so0), (unsigned*)((char*)(P) + tid_ * 16), 16, 0, 0); \
;     __builtin_amdgcn_global_load_lds((const GAS unsigned*)(_g + so1), (unsigned*)((char*)(P) + tid_ * 16 + 8192), 16, 0, 0); } while (0)
; template <int K, int LD = K>
; __device__ __forceinline__ void gemm_prefetch(const GAS bf16* A, const GAS bf16* Bt, int brow, int bcol) {
;   bf16* shm = (bf16*)smem_raw;
;   const int tid_ = otid();
;   unsigned so0, so1;
;   { int r_, c_; stage_rc(tid_ * 16, r_, c_); so0 = (unsigned)(r_ * LD + c_) * 2u; stage_rc(tid_ * 16 + 8192, r_, c_); so1 = (unsigned)(r_ * LD + c_) * 2u; }
;   const GAS char* pA0 = (const GAS char*)A + (long)brow * LD * 2; const GAS char* pA1 = pA0 + (long)HALF * LD * 2;
;   const GAS char* pB0 = (const GAS char*)Bt + (long)bcol * LD * 2; const GAS char* pB1 = pB0 + (long)HALF * LD * 2;
;   asm volatile("" : "+s"(pA0), "+s"(pA1), "+s"(pB0), "+s"(pB1));
;   STAGE(SB(0, 0), pB0, 0); STAGE(SA(0, 0), pA0, 0);
;   STAGE(SB(0, 1), pB1, 0); STAGE(SA(0, 1), pA1, 0);
;   STAGE(SB(1, 0), pB0, 1); STAGE(SA(1, 0), pA0, 1); STAGE(SB(1, 1), pB1, 1);
; __device__ __forceinline__ void load_rr(const GAS float* ssq, int brow, int par) {
;   float* rr = (float*)(smem_raw + LDS_RR) + par * 256;
;   const int tx = otid();
;   if (tx < 256) {
;     const GAS f32x4* s = (const GAS f32x4*)(ssq + (size_t)(brow + tx) * 16);
;     f32x4 a = s[0], b = s[1], c = s[2], d = s[3];
;     float t = ((a.x + a.y) + (a.z + a.w)) + ((b.x + b.y) + (b.z + b.w)) + ((c.x + c.y) + (c.z + c.w)) + ((d.x + d.y) + (d.z + d.w));
;     rr[tx] = rsqrtf(t * (1.f / DM) + EPS);
;   }
.LBB0_92:
	s_or_b64 exec, exec, s[14:15]
	v_readfirstlane_b32 s14, v171
	s_add_i32 s3, s14, s3
	s_cmpk_gt_i32 s3, 0x57f
	s_cselect_b64 s[14:15], -1, 0
	s_and_b64 vcc, exec, s[14:15]
	s_mov_b32 s22, s41
	s_cbranch_vccnz .LBB0_85
	v_mov_b32_e32 v130, v170
	s_mul_hi_i32 s17, s3, 0x2e8ba2e9
	v_ashrrev_i32_e32 v132, 31, v130
	v_lshrrev_b32_e32 v132, 26, v132
	v_lshlrev_b32_e32 v148, 4, v130
	v_add_u32_e32 v132, v130, v132
	v_bfe_i32 v130, v130, 27, 1
	v_lshrrev_b32_e32 v130, 22, v130
	v_add_u32_e32 v130, v148, v130
	v_and_b32_e32 v130, 0xfffffc00, v130
	v_sub_u32_e32 v130, v148, v130
	v_lshrrev_b32_e32 v133, 4, v130
	v_bitop3_b32 v133, v133, v130, 32 bitop3:0x6c
	v_ashrrev_i32_e32 v130, 31, v130
	v_lshrrev_b32_e32 v130, 26, v130
	v_add_u32_e32 v130, v133, v130
	v_ashrrev_i32_e32 v130, 6, v130
	v_ashrrev_i32_e32 v132, 6, v132
	v_mul_i32_i24_e32 v137, 64, v130
	v_lshlrev_b32_e32 v136, 3, v132
	v_lshlrev_b32_e32 v132, 5, v132
	v_sub_u32_e32 v133, v133, v137
	s_lshr_b32 s18, s17, 31
	s_ashr_i32 s17, s17, 5
	v_and_b32_e32 v136, 0x1ffff0, v136
	v_and_b32_e32 v132, 32, v132
	v_ashrrev_i16_sdwa v133, v134, sext(v133) dst_sel:DWORD dst_unused:UNUSED_PAD src0_sel:DWORD src1_sel:BYTE_0
	s_add_i32 s17, s17, s18
	v_add_u32_sdwa v132, v132, sext(v133) dst_sel:DWORD dst_unused:UNUSED_PAD src0_sel:DWORD src1_sel:WORD_0
	v_add_lshl_u32 v130, v130, v136, 11
	s_mul_i32 s18, s17, 0xb0
	v_lshl_add_u32 v130, v132, 1, v130
	v_add_u32_e32 v132, 0x2000, v148
	s_sub_i32 s18, s3, s18
	v_ashrrev_i32_e32 v133, 31, v132
	s_lshl_b32 s17, s17, 3
	s_and_b32 s19, s18, 7
	v_lshrrev_b32_e32 v133, 22, v133
	s_or_b32 s28, s19, s17
	v_add_u32_e32 v133, v132, v133
	s_ashr_i32 s22, s18, 3
	s_lshl_b32 s18, s28, 8
	v_ashrrev_i32_e32 v133, 10, v133
	v_mul_i32_i24_e32 v136, 0x400, v133
	s_ashr_i32 s19, s18, 31
	s_lshl_b32 s20, s22, 8
	v_sub_u32_e32 v132, v132, v136
	s_lshl_b64 s[24:25], s[18:19], 11
	v_lshrrev_b32_e32 v136, 4, v132
	s_add_u32 s24, s26, s24
	v_bitop3_b32 v132, v136, v132, 32 bitop3:0x6c
	s_addc_u32 s25, s27, s25
	v_ashrrev_i32_e32 v137, 31, v132
	s_add_u32 s42, s24, 0x40000
	v_lshrrev_b32_e32 v137, 26, v137
	s_addc_u32 s43, s25, 0
	s_ashr_i32 s21, s20, 31
	v_add_u32_e32 v137, v132, v137
	s_lshl_b64 s[20:21], s[20:21], 11
	v_lshrrev_b32_e32 v138, 6, v137
	v_and_b32_e32 v137, 0xc0, v137
	s_add_u32 s20, s4, s20
	v_lshlrev_b32_e32 v136, 3, v133
	v_lshlrev_b32_e32 v133, 5, v133
	v_sub_u32_e32 v132, v132, v137
	s_addc_u32 s21, s5, s21
	v_add_u32_e32 v140, s29, v148
	v_and_b32_e32 v136, 0x1ffff0, v136
	v_and_b32_e32 v133, 32, v133
	v_ashrrev_i16_sdwa v132, v134, sext(v132) dst_sel:DWORD dst_unused:UNUSED_PAD src0_sel:DWORD src1_sel:BYTE_0
	s_add_u32 s44, s20, 0x40000
	v_readfirstlane_b32 s17, v140
	v_add_u32_e32 v140, 0x2000, v140
	v_add_u32_sdwa v132, v133, sext(v132) dst_sel:DWORD dst_unused:UNUSED_PAD src0_sel:DWORD src1_sel:WORD_0
	v_add_lshl_u32 v133, v138, v136, 11
	s_addc_u32 s45, s21, 0
	s_mov_b32 m0, s17
	v_readfirstlane_b32 s17, v140
	v_add_u32_e32 v149, 0x100, v148
	v_lshl_add_u32 v132, v132, 1, v133
	v_add_u32_e32 v144, 0x2000, v149
	global_load_lds_dwordx4 v130, s[20:21]
	s_mov_b32 m0, s17
	v_readfirstlane_b32 s17, v149
	v_mov_b32_e32 v133, v131
	global_load_lds_dwordx4 v132, s[20:21]
	s_mov_b32 m0, s17
	v_readfirstlane_b32 s17, v144
	v_add_u32_e32 v150, s30, v148
	v_lshl_add_u64 v[138:139], s[20:21], 0, v[132:133]
	global_load_lds_dwordx4 v130, s[24:25]
	v_lshl_add_u64 v[142:143], s[24:25], 0, v[132:133]
	s_mov_b32 m0, s17
	v_readfirstlane_b32 s17, v150
	v_lshl_add_u64 v[146:147], s[44:45], 0, v[132:133]
	v_add_u32_e32 v133, 0x2000, v150
	global_load_lds_dwordx4 v132, s[24:25]
	s_mov_b32 m0, s17
	v_readfirstlane_b32 s17, v133
	v_add_u32_e32 v133, 0x4000, v149
	global_load_lds_dwordx4 v130, s[44:45]
	s_mov_b32 m0, s17
	v_readfirstlane_b32 s17, v133
	global_load_lds_dwordx4 v132, s[44:45]
	s_mov_b32 m0, s17
	v_lshl_add_u64 v[136:137], s[20:21], 0, v[130:131]
	v_lshl_add_u64 v[140:141], s[24:25], 0, v[130:131]
	v_lshl_add_u64 v[144:145], s[44:45], 0, v[130:131]
	global_load_lds_dwordx4 v130, s[42:43]
	v_add_u32_e32 v130, 0x6000, v149
	s_nop 0
	v_readfirstlane_b32 s17, v130
	v_add_u32_e32 v130, s31, v148
	s_mov_b32 m0, s17
	v_readfirstlane_b32 s17, v130
	v_add_u32_e32 v130, 0x2000, v130
	global_load_lds_dwordx4 v132, s[42:43]
	v_lshl_add_u64 v[132:133], v[136:137], 0, s[8:9]
	s_mov_b32 m0, s17
	v_readfirstlane_b32 s17, v130
	v_add_u32_e32 v130, 0x8000, v149
	global_load_lds_dwordx4 v[132:133], off
	v_lshl_add_u64 v[132:133], v[138:139], 0, s[8:9]
	s_mov_b32 m0, s17
	v_readfirstlane_b32 s17, v130
	v_add_u32_e32 v130, 0xa000, v149
	global_load_lds_dwordx4 v[132:133], off
	v_lshl_add_u64 v[132:133], v[140:141], 0, s[8:9]
	s_mov_b32 m0, s17
	v_readfirstlane_b32 s17, v130
	v_add_u32_e32 v130, s33, v148
	global_load_lds_dwordx4 v[132:133], off
	v_lshl_add_u64 v[132:133], v[142:143], 0, s[8:9]
	s_mov_b32 m0, s17
	v_readfirstlane_b32 s17, v130
	v_add_u32_e32 v130, 0x2000, v130
	global_load_lds_dwordx4 v[132:133], off
	v_lshl_add_u64 v[132:133], v[144:145], 0, s[8:9]
	s_mov_b32 m0, s17
	v_readfirstlane_b32 s17, v130
	global_load_lds_dwordx4 v[132:133], off
	v_lshl_add_u64 v[132:133], v[146:147], 0, s[8:9]
	s_mov_b32 m0, s17
	v_mov_b32_e32 v130, v170
	global_load_lds_dwordx4 v[132:133], off
	s_nop 0
	v_cmp_gt_i32_e32 vcc, s34, v130
	s_and_saveexec_b64 s[20:21], vcc
	s_cbranch_execz .LBB0_84
	v_add_u32_e32 v132, s18, v130
	v_ashrrev_i32_e32 v133, 31, v132
	v_lshlrev_b64 v[132:133], 6, v[132:133]
	v_lshl_add_u64 v[132:133], s[6:7], 0, v[132:133]
	global_load_dwordx4 v[136:139], v[132:133], off
	global_load_dwordx4 v[140:143], v[132:133], off offset:16
	global_load_dwordx4 v[144:147], v[132:133], off offset:32
	global_load_dwordx4 v[148:151], v[132:133], off offset:48
	s_branch .LBB0_84

; #define STAGE(P, GP, ktrel) do { const GAS char* _g = (GP) + (ktrel) * (BK * 2); \
;     __builtin_amdgcn_global_load_lds((const GAS unsigned*)(_g + so0), (unsigned*)((char*)(P) + tid_ * 16), 16, 0, 0); \
;     __builtin_amdgcn_global_load_lds((const GAS unsigned*)(_g + so1), (unsigned*)((char*)(P) + tid_ * 16 + 8192), 16, 0, 0); } while (0)
; #define WAIT_V(n) asm volatile("s_waitcnt vmcnt(" #n ")" ::: "memory")
; #define WAIT_L(n) asm volatile("s_waitcnt lgkmcnt(" #n ")" ::: "memory")
; #define BAR __builtin_amdgcn_s_barrier()
; #define SCHED __builtin_amdgcn_sched_barrier(0)
; #define LDA(dst, b, h) for (int m = 0; m < 4; ++m) for (int k = 0; k < 2; ++k) \
;     dst[m][k] = *reinterpret_cast<const bf16x8*>((char*)SA(b, h) + lds_byte(wr * 64 + m * 16 + fr, k * 32 + fq * 8))
; #define LDB(dst, b, h) for (int n = 0; n < 2; ++n) for (int k = 0; k < 2; ++k) \
;     dst[n][k] = *reinterpret_cast<const bf16x8*>((char*)SB(b, h) + lds_byte(wc * 32 + n * 16 + fr, k * 32 + fq * 8))
; #define MMA(ai, bj, At_, Bt_) do { __builtin_amdgcn_s_setprio(1); \
;     for (int m = 0; m < 4; ++m) for (int n = 0; n < 2; ++n) for (int k = 0; k < 2; ++k) \
;       acc[ai][bj][m][n] = __builtin_amdgcn_mfma_f32_16x16x32_bf16(At_[m][k], Bt_[n][k], acc[ai][bj][m][n], 0, 0, 0); \
;     __builtin_amdgcn_s_setprio(0); } while (0)
; template <int K, int LD = K>
; __device__ __forceinline__ void gemm_main(const GAS bf16* A, const GAS bf16* Bt, int brow, int bcol, f32x4 (&acc)[2][2][4][2]) {
;     ...
;     LDB(B0, 0, 0); SCHED; LDA(At, 0, 0); STAGE(SA(1, 1), pA1, 1);
;     WAIT_L(8); BAR; WAIT_L(0); MMA(0, 0, At, B0); BAR; SCHED;
;     LDB(B1, 0, 1); STAGE(SB(0, 0), pB0, 2);
;     BAR; WAIT_L(0); MMA(0, 1, At, B1); BAR;
;     LDA(At, 0, 1); STAGE(SA(0, 0), pA0, 2);
;     BAR; WAIT_L(0); MMA(1, 0, At, B0); BAR; SCHED;
;     STAGE(SB(0, 1), pB1, 2);
;     WAIT_V(6); BAR; MMA(1, 1, At, B1); BAR;
.LBB0_709:
	ds_read_b128 v[146:149], v143
	ds_read_b128 v[150:153], v143 offset:1024
	ds_read_b128 v[154:157], v143 offset:2048
	ds_read_b128 v[158:161], v143 offset:3072
	v_add_u32_e32 v230, 0x100, v141
	v_add_u32_e32 v144, 0xc000, v230
	v_lshl_add_u64 v[214:215], s[20:21], 0, v[130:131]
	v_readfirstlane_b32 s30, v144
	v_add_u32_e32 v145, 0xe000, v230
	v_lshl_add_u64 v[198:199], v[214:215], 0, s[6:7]
	s_mov_b32 m0, s30
	v_lshl_add_u64 v[216:217], s[20:21], 0, v[132:133]
	v_readfirstlane_b32 s30, v145
	ds_read_b128 v[162:165], v138
	ds_read_b128 v[166:169], v138 offset:1024
	ds_read_b128 v[174:177], v137
	ds_read_b128 v[178:181], v137 offset:1024
	ds_read_b128 v[182:185], v136
	ds_read_b128 v[186:189], v136 offset:1024
	ds_read_b128 v[190:193], v135
	ds_read_b128 v[194:197], v135 offset:1024
	global_load_lds_dwordx4 v[198:199], off
	v_lshl_add_u64 v[198:199], v[216:217], 0, s[6:7]
	s_mov_b32 m0, s30
	s_nop 0
	global_load_lds_dwordx4 v[198:199], off
	s_waitcnt lgkmcnt(8)
	s_waitcnt vmcnt(10)
	s_barrier
	s_waitcnt lgkmcnt(0)
	s_waitcnt lgkmcnt(0)
	v_mfma_f32_16x16x32_bf16 v[126:129], v[146:149], v[162:165], v[126:129]
	v_mfma_f32_16x16x32_bf16 v[122:125], v[154:157], v[162:165], v[122:125]
	v_mfma_f32_16x16x32_bf16 v[118:121], v[146:149], v[174:177], v[118:121]
	v_mfma_f32_16x16x32_bf16 v[114:117], v[154:157], v[174:177], v[114:117]
	v_mfma_f32_16x16x32_bf16 v[110:113], v[146:149], v[182:185], v[110:113]
	v_mfma_f32_16x16x32_bf16 v[106:109], v[154:157], v[182:185], v[106:109]
	v_mfma_f32_16x16x32_bf16 v[102:105], v[146:149], v[190:193], v[102:105]
	v_mfma_f32_16x16x32_bf16 v[98:101], v[154:157], v[190:193], v[98:101]
	v_mfma_f32_16x16x32_bf16 v[126:129], v[150:153], v[166:169], v[126:129]
	v_mfma_f32_16x16x32_bf16 v[122:125], v[158:161], v[166:169], v[122:125]
	v_mfma_f32_16x16x32_bf16 v[118:121], v[150:153], v[178:181], v[118:121]
	v_mfma_f32_16x16x32_bf16 v[114:117], v[158:161], v[178:181], v[114:117]
	v_mfma_f32_16x16x32_bf16 v[110:113], v[150:153], v[186:189], v[110:113]
	v_mfma_f32_16x16x32_bf16 v[106:109], v[158:161], v[186:189], v[106:109]
	v_mfma_f32_16x16x32_bf16 v[102:105], v[150:153], v[194:197], v[102:105]
	v_mfma_f32_16x16x32_bf16 v[98:101], v[158:161], v[194:197], v[98:101]
	s_barrier
	v_add_u32_e32 v224, s47, v141
	v_lshl_add_u64 v[218:219], s[28:29], 0, v[130:131]
	v_readfirstlane_b32 s30, v224
	v_lshl_add_u64 v[220:221], v[218:219], 0, s[10:11]
	s_mov_b32 m0, s30
	v_add_u32_e32 v224, 0x2000, v224
	ds_read_b128 v[198:201], v142
	ds_read_b128 v[202:205], v142 offset:1024
	ds_read_b128 v[206:209], v142 offset:2048
	ds_read_b128 v[210:213], v142 offset:3072
	global_load_lds_dwordx4 v[220:221], off
	v_lshl_add_u64 v[220:221], s[28:29], 0, v[132:133]
	v_readfirstlane_b32 s30, v224
	v_lshl_add_u64 v[222:223], v[220:221], 0, s[10:11]
	s_mov_b32 m0, s30
	s_add_u32 s28, s28, 0x100
	global_load_lds_dwordx4 v[222:223], off
	s_waitcnt vmcnt(10)
	s_barrier
	s_waitcnt lgkmcnt(0)
	s_addc_u32 s29, s29, 0
	s_waitcnt lgkmcnt(0)
	v_mfma_f32_16x16x32_bf16 v[94:97], v[198:201], v[162:165], v[94:97]
	v_mfma_f32_16x16x32_bf16 v[90:93], v[206:209], v[162:165], v[90:93]
	v_mfma_f32_16x16x32_bf16 v[86:89], v[198:201], v[174:177], v[86:89]
	v_mfma_f32_16x16x32_bf16 v[82:85], v[206:209], v[174:177], v[82:85]
	v_mfma_f32_16x16x32_bf16 v[78:81], v[198:201], v[182:185], v[78:81]
	v_mfma_f32_16x16x32_bf16 v[74:77], v[206:209], v[182:185], v[74:77]
	v_mfma_f32_16x16x32_bf16 v[70:73], v[198:201], v[190:193], v[70:73]
	v_mfma_f32_16x16x32_bf16 v[66:69], v[206:209], v[190:193], v[66:69]
	v_mfma_f32_16x16x32_bf16 v[94:97], v[202:205], v[166:169], v[94:97]
	v_mfma_f32_16x16x32_bf16 v[90:93], v[210:213], v[166:169], v[90:93]
	v_mfma_f32_16x16x32_bf16 v[86:89], v[202:205], v[178:181], v[86:89]
	v_mfma_f32_16x16x32_bf16 v[82:85], v[210:213], v[178:181], v[82:85]
	v_mfma_f32_16x16x32_bf16 v[78:81], v[202:205], v[186:189], v[78:81]
	v_mfma_f32_16x16x32_bf16 v[74:77], v[210:213], v[186:189], v[74:77]
	v_mfma_f32_16x16x32_bf16 v[70:73], v[202:205], v[194:197], v[70:73]
	v_mfma_f32_16x16x32_bf16 v[66:69], v[210:213], v[194:197], v[66:69]
	v_lshl_add_u64 v[222:223], s[26:27], 0, v[130:131]
	v_readfirstlane_b32 s30, v230
	v_lshl_add_u64 v[224:225], v[222:223], 0, s[10:11]
	s_mov_b32 m0, s30
	v_add_u32_e32 v228, 0x2000, v230
	s_barrier
	ds_read_b128 v[162:165], v138 offset:16384
	ds_read_b128 v[166:169], v138 offset:17408
	ds_read_b128 v[174:177], v137 offset:16384
	ds_read_b128 v[178:181], v137 offset:17408
	ds_read_b128 v[182:185], v136 offset:16384
	ds_read_b128 v[186:189], v136 offset:17408
	ds_read_b128 v[190:193], v135 offset:16384
	ds_read_b128 v[194:197], v135 offset:17408
	global_load_lds_dwordx4 v[224:225], off
	v_lshl_add_u64 v[224:225], s[26:27], 0, v[132:133]
	v_readfirstlane_b32 s30, v228
	v_lshl_add_u64 v[226:227], v[224:225], 0, s[10:11]
	s_mov_b32 m0, s30
	s_add_u32 s26, s26, 0x100
	global_load_lds_dwordx4 v[226:227], off
	s_barrier
	s_waitcnt lgkmcnt(0)
	s_addc_u32 s27, s27, 0
	s_waitcnt lgkmcnt(0)
	v_mfma_f32_16x16x32_bf16 v[62:65], v[146:149], v[162:165], v[62:65]
	v_mfma_f32_16x16x32_bf16 v[58:61], v[154:157], v[162:165], v[58:61]
	v_mfma_f32_16x16x32_bf16 v[54:57], v[146:149], v[174:177], v[54:57]
	v_mfma_f32_16x16x32_bf16 v[50:53], v[154:157], v[174:177], v[50:53]
	v_mfma_f32_16x16x32_bf16 v[46:49], v[146:149], v[182:185], v[46:49]
	v_mfma_f32_16x16x32_bf16 v[42:45], v[154:157], v[182:185], v[42:45]
	v_mfma_f32_16x16x32_bf16 v[38:41], v[146:149], v[190:193], v[38:41]
	v_mfma_f32_16x16x32_bf16 v[34:37], v[154:157], v[190:193], v[34:37]
	v_mfma_f32_16x16x32_bf16 v[62:65], v[150:153], v[166:169], v[62:65]
	v_mfma_f32_16x16x32_bf16 v[58:61], v[158:161], v[166:169], v[58:61]
	v_mfma_f32_16x16x32_bf16 v[54:57], v[150:153], v[178:181], v[54:57]
	v_mfma_f32_16x16x32_bf16 v[50:53], v[158:161], v[178:181], v[50:53]
	v_mfma_f32_16x16x32_bf16 v[46:49], v[150:153], v[186:189], v[46:49]
	v_mfma_f32_16x16x32_bf16 v[42:45], v[158:161], v[186:189], v[42:45]
	v_mfma_f32_16x16x32_bf16 v[38:41], v[150:153], v[194:197], v[38:41]
	v_mfma_f32_16x16x32_bf16 v[34:37], v[158:161], v[194:197], v[34:37]
	s_barrier
; #define STAGE(P, GP, ktrel) do { const GAS char* _g = (GP) + (ktrel) * (BK * 2); \
;     __builtin_amdgcn_global_load_lds((const GAS unsigned*)(_g + so0), (unsigned*)((char*)(P) + tid_ * 16), 16, 0, 0); \
;     __builtin_amdgcn_global_load_lds((const GAS unsigned*)(_g + so1), (unsigned*)((char*)(P) + tid_ * 16 + 8192), 16, 0, 0); } while (0)
; #define WAIT_V(n) asm volatile("s_waitcnt vmcnt(" #n ")" ::: "memory")
; #define WAIT_L(n) asm volatile("s_waitcnt lgkmcnt(" #n ")" ::: "memory")
; #define BAR __builtin_amdgcn_s_barrier()
; #define SCHED __builtin_amdgcn_sched_barrier(0)
; #define LDA(dst, b, h) for (int m = 0; m < 4; ++m) for (int k = 0; k < 2; ++k) \
;     dst[m][k] = *reinterpret_cast<const bf16x8*>((char*)SA(b, h) + lds_byte(wr * 64 + m * 16 + fr, k * 32 + fq * 8))
; #define LDB(dst, b, h) for (int n = 0; n < 2; ++n) for (int k = 0; k < 2; ++k) \
;     dst[n][k] = *reinterpret_cast<const bf16x8*>((char*)SB(b, h) + lds_byte(wc * 32 + n * 16 + fr, k * 32 + fq * 8))
; #define MMA(ai, bj, At_, Bt_) do { __builtin_amdgcn_s_setprio(1); \
;     for (int m = 0; m < 4; ++m) for (int n = 0; n < 2; ++n) for (int k = 0; k < 2; ++k) \
;       acc[ai][bj][m][n] = __builtin_amdgcn_mfma_f32_16x16x32_bf16(At_[m][k], Bt_[n][k], acc[ai][bj][m][n], 0, 0, 0); \
;     __builtin_amdgcn_s_setprio(0); } while (0)
; template <int K, int LD = K>
; __device__ __forceinline__ void gemm_main(const GAS bf16* A, const GAS bf16* Bt, int brow, int bcol, f32x4 (&acc)[2][2][4][2]) {
;     ...
;     WAIT_V(6); BAR; MMA(1, 1, At, B1); BAR;
;     LDB(B0, 1, 0); SCHED; LDA(At, 1, 0); STAGE(SA(0, 1), pA1, 2);
;     WAIT_L(8); BAR; WAIT_L(0); MMA(0, 0, At, B0); BAR; SCHED;
;     LDB(B1, 1, 1); STAGE(SB(1, 0), pB0, 3);
;     BAR; WAIT_L(0); MMA(0, 1, At, B1); BAR;
;     LDA(At, 1, 1); STAGE(SA(1, 0), pA0, 3);
;     BAR; WAIT_L(0); MMA(1, 0, At, B0); BAR; SCHED;
	v_add_u32_e32 v148, s48, v141
	v_lshl_add_u64 v[226:227], s[24:25], 0, v[130:131]
	v_readfirstlane_b32 s30, v148
	v_add_u32_e32 v148, 0x2000, v148
	v_lshl_add_u64 v[146:147], v[226:227], 0, s[10:11]
	s_mov_b32 m0, s30
	v_lshl_add_u64 v[228:229], s[24:25], 0, v[132:133]
	v_readfirstlane_b32 s30, v148
	global_load_lds_dwordx4 v[146:147], off
	v_lshl_add_u64 v[146:147], v[228:229], 0, s[10:11]
	s_mov_b32 m0, s30
	s_add_u32 s24, s24, 0x100
	global_load_lds_dwordx4 v[146:147], off
	s_waitcnt vmcnt(10)
	s_addc_u32 s25, s25, 0
	s_barrier
	v_mfma_f32_16x16x32_bf16 v[30:33], v[198:201], v[162:165], v[30:33]
	v_mfma_f32_16x16x32_bf16 v[26:29], v[206:209], v[162:165], v[26:29]
	v_mfma_f32_16x16x32_bf16 v[22:25], v[198:201], v[174:177], v[22:25]
	v_mfma_f32_16x16x32_bf16 v[18:21], v[206:209], v[174:177], v[18:21]
	v_mfma_f32_16x16x32_bf16 v[14:17], v[198:201], v[182:185], v[14:17]
	v_mfma_f32_16x16x32_bf16 v[10:13], v[206:209], v[182:185], v[10:13]
	v_mfma_f32_16x16x32_bf16 v[6:9], v[198:201], v[190:193], v[6:9]
	v_mfma_f32_16x16x32_bf16 v[2:5], v[206:209], v[190:193], v[2:5]
	v_mfma_f32_16x16x32_bf16 v[30:33], v[202:205], v[166:169], v[30:33]
	v_mfma_f32_16x16x32_bf16 v[26:29], v[210:213], v[166:169], v[26:29]
	v_mfma_f32_16x16x32_bf16 v[22:25], v[202:205], v[178:181], v[22:25]
	v_mfma_f32_16x16x32_bf16 v[18:21], v[210:213], v[178:181], v[18:21]
	v_mfma_f32_16x16x32_bf16 v[14:17], v[202:205], v[186:189], v[14:17]
	v_mfma_f32_16x16x32_bf16 v[10:13], v[210:213], v[186:189], v[10:13]
	v_mfma_f32_16x16x32_bf16 v[6:9], v[202:205], v[194:197], v[6:9]
	v_mfma_f32_16x16x32_bf16 v[2:5], v[210:213], v[194:197], v[2:5]
	s_barrier
	ds_read_b128 v[146:149], v140
	ds_read_b128 v[150:153], v140 offset:1024
	ds_read_b128 v[154:157], v140 offset:2048
	ds_read_b128 v[158:161], v140 offset:3072
	v_add_u32_e32 v200, 0x4000, v230
	v_lshl_add_u64 v[198:199], v[214:215], 0, s[10:11]
	v_readfirstlane_b32 s30, v200
	v_add_u32_e32 v200, 0x6000, v230
	s_mov_b32 m0, s30
	v_readfirstlane_b32 s30, v200
	ds_read_b128 v[162:165], v138 offset:32768
	ds_read_b128 v[166:169], v138 offset:33792
	ds_read_b128 v[174:177], v137 offset:32768
	ds_read_b128 v[178:181], v137 offset:33792
	ds_read_b128 v[182:185], v136 offset:32768
	ds_read_b128 v[186:189], v136 offset:33792
	ds_read_b128 v[190:193], v135 offset:32768
	ds_read_b128 v[194:197], v135 offset:33792
	global_load_lds_dwordx4 v[198:199], off
	v_lshl_add_u64 v[198:199], v[216:217], 0, s[10:11]
	s_mov_b32 m0, s30
	s_add_u32 s20, s20, 0x100
	global_load_lds_dwordx4 v[198:199], off
	s_waitcnt lgkmcnt(8)
	s_waitcnt vmcnt(10)
	s_barrier
	s_waitcnt lgkmcnt(0)
	s_addc_u32 s21, s21, 0
	s_waitcnt lgkmcnt(0)
	v_mfma_f32_16x16x32_bf16 v[126:129], v[146:149], v[162:165], v[126:129]
	v_mfma_f32_16x16x32_bf16 v[122:125], v[154:157], v[162:165], v[122:125]
	v_mfma_f32_16x16x32_bf16 v[118:121], v[146:149], v[174:177], v[118:121]
	v_mfma_f32_16x16x32_bf16 v[114:117], v[154:157], v[174:177], v[114:117]
	v_mfma_f32_16x16x32_bf16 v[110:113], v[146:149], v[182:185], v[110:113]
	v_mfma_f32_16x16x32_bf16 v[106:109], v[154:157], v[182:185], v[106:109]
	v_mfma_f32_16x16x32_bf16 v[102:105], v[146:149], v[190:193], v[102:105]
	v_mfma_f32_16x16x32_bf16 v[98:101], v[154:157], v[190:193], v[98:101]
	v_mfma_f32_16x16x32_bf16 v[126:129], v[150:153], v[166:169], v[126:129]
	v_mfma_f32_16x16x32_bf16 v[122:125], v[158:161], v[166:169], v[122:125]
	v_mfma_f32_16x16x32_bf16 v[118:121], v[150:153], v[178:181], v[118:121]
	v_mfma_f32_16x16x32_bf16 v[114:117], v[158:161], v[178:181], v[114:117]
	v_mfma_f32_16x16x32_bf16 v[110:113], v[150:153], v[186:189], v[110:113]
	v_mfma_f32_16x16x32_bf16 v[106:109], v[158:161], v[186:189], v[106:109]
	v_mfma_f32_16x16x32_bf16 v[102:105], v[150:153], v[194:197], v[102:105]
	v_mfma_f32_16x16x32_bf16 v[98:101], v[158:161], v[194:197], v[98:101]
	s_barrier
	v_add_u32_e32 v216, s49, v141
	v_lshl_add_u64 v[214:215], v[218:219], 0, s[12:13]
	v_readfirstlane_b32 s30, v216
	v_add_u32_e32 v216, 0x2000, v216
	s_mov_b32 m0, s30
	v_readfirstlane_b32 s30, v216
	ds_read_b128 v[198:201], v139
	ds_read_b128 v[202:205], v139 offset:1024
	ds_read_b128 v[206:209], v139 offset:2048
	ds_read_b128 v[210:213], v139 offset:3072
	global_load_lds_dwordx4 v[214:215], off
	v_lshl_add_u64 v[214:215], v[220:221], 0, s[12:13]
	s_mov_b32 m0, s30
	s_nop 0
	global_load_lds_dwordx4 v[214:215], off
	s_waitcnt vmcnt(10)
	s_barrier
	s_waitcnt lgkmcnt(0)
	s_waitcnt lgkmcnt(0)
	v_mfma_f32_16x16x32_bf16 v[94:97], v[198:201], v[162:165], v[94:97]
	v_mfma_f32_16x16x32_bf16 v[90:93], v[206:209], v[162:165], v[90:93]
	v_mfma_f32_16x16x32_bf16 v[86:89], v[198:201], v[174:177], v[86:89]
	v_mfma_f32_16x16x32_bf16 v[82:85], v[206:209], v[174:177], v[82:85]
	v_mfma_f32_16x16x32_bf16 v[78:81], v[198:201], v[182:185], v[78:81]
	v_mfma_f32_16x16x32_bf16 v[74:77], v[206:209], v[182:185], v[74:77]
	v_mfma_f32_16x16x32_bf16 v[70:73], v[198:201], v[190:193], v[70:73]
	v_mfma_f32_16x16x32_bf16 v[66:69], v[206:209], v[190:193], v[66:69]
	v_mfma_f32_16x16x32_bf16 v[94:97], v[202:205], v[166:169], v[94:97]
	v_mfma_f32_16x16x32_bf16 v[90:93], v[210:213], v[166:169], v[90:93]
	v_mfma_f32_16x16x32_bf16 v[86:89], v[202:205], v[178:181], v[86:89]
	v_mfma_f32_16x16x32_bf16 v[82:85], v[210:213], v[178:181], v[82:85]
	v_mfma_f32_16x16x32_bf16 v[78:81], v[202:205], v[186:189], v[78:81]
	v_mfma_f32_16x16x32_bf16 v[74:77], v[210:213], v[186:189], v[74:77]
	v_mfma_f32_16x16x32_bf16 v[70:73], v[202:205], v[194:197], v[70:73]
	v_mfma_f32_16x16x32_bf16 v[66:69], v[210:213], v[194:197], v[66:69]
	v_add_u32_e32 v216, 0x8000, v230
	v_lshl_add_u64 v[214:215], v[222:223], 0, s[12:13]
	v_readfirstlane_b32 s30, v216
	v_add_u32_e32 v216, 0xa000, v230
	s_mov_b32 m0, s30
	v_readfirstlane_b32 s30, v216
	s_barrier
; #define STAGE(P, GP, ktrel) do { const GAS char* _g = (GP) + (ktrel) * (BK * 2); \
;     __builtin_amdgcn_global_load_lds((const GAS unsigned*)(_g + so0), (unsigned*)((char*)(P) + tid_ * 16), 16, 0, 0); \
;     __builtin_amdgcn_global_load_lds((const GAS unsigned*)(_g + so1), (unsigned*)((char*)(P) + tid_ * 16 + 8192), 16, 0, 0); } while (0)
; #define WAIT_V(n) asm volatile("s_waitcnt vmcnt(" #n ")" ::: "memory")
; #define WAIT_L(n) asm volatile("s_waitcnt lgkmcnt(" #n ")" ::: "memory")
; #define BAR __builtin_amdgcn_s_barrier()
; #define SCHED __builtin_amdgcn_sched_barrier(0)
; #define LDA(dst, b, h) for (int m = 0; m < 4; ++m) for (int k = 0; k < 2; ++k) \
;     dst[m][k] = *reinterpret_cast<const bf16x8*>((char*)SA(b, h) + lds_byte(wr * 64 + m * 16 + fr, k * 32 + fq * 8))
; #define LDB(dst, b, h) for (int n = 0; n < 2; ++n) for (int k = 0; k < 2; ++k) \
;     dst[n][k] = *reinterpret_cast<const bf16x8*>((char*)SB(b, h) + lds_byte(wc * 32 + n * 16 + fr, k * 32 + fq * 8))
; #define MMA(ai, bj, At_, Bt_) do { __builtin_amdgcn_s_setprio(1); \
;     for (int m = 0; m < 4; ++m) for (int n = 0; n < 2; ++n) for (int k = 0; k < 2; ++k) \
;       acc[ai][bj][m][n] = __builtin_amdgcn_mfma_f32_16x16x32_bf16(At_[m][k], Bt_[n][k], acc[ai][bj][m][n], 0, 0, 0); \
;     __builtin_amdgcn_s_setprio(0); } while (0)
; template <int K, int LD = K>
; __device__ __forceinline__ void gemm_main(const GAS bf16* A, const GAS bf16* Bt, int brow, int bcol, f32x4 (&acc)[2][2][4][2]) {
;     ...
;     LDA(At, 1, 1); STAGE(SA(1, 0), pA0, 3);
;     BAR; WAIT_L(0); MMA(1, 0, At, B0); BAR; SCHED;
;     STAGE(SB(1, 1), pB1, 3);
;     WAIT_V(6); BAR; MMA(1, 1, At, B1); BAR;
;     pA0 += 4 * BK; pA1 += 4 * BK; pB0 += 4 * BK; pB1 += 4 * BK;
;     asm volatile("" : "+s"(pA0), "+s"(pA1), "+s"(pB0), "+s"(pB1));
;   }
;   { LDB(B0, 0, 0); LDA(At, 0, 0); STAGE(SA(1, 1), pA1, 1);
;     BAR; WAIT_L(0); MMA(0, 0, At, B0); BAR;
;     LDB(B1, 0, 1); BAR; WAIT_L(0); MMA(0, 1, At, B1); BAR;
	ds_read_b128 v[162:165], v138 offset:49152
	ds_read_b128 v[166:169], v138 offset:50176
	ds_read_b128 v[174:177], v137 offset:49152
	ds_read_b128 v[178:181], v137 offset:50176
	ds_read_b128 v[182:185], v136 offset:49152
	ds_read_b128 v[186:189], v136 offset:50176
	ds_read_b128 v[190:193], v135 offset:49152
	ds_read_b128 v[194:197], v135 offset:50176
	global_load_lds_dwordx4 v[214:215], off
	v_lshl_add_u64 v[214:215], v[224:225], 0, s[12:13]
	s_mov_b32 m0, s30
	s_nop 0
	global_load_lds_dwordx4 v[214:215], off
	s_barrier
	s_waitcnt lgkmcnt(0)
	s_waitcnt lgkmcnt(0)
	v_mfma_f32_16x16x32_bf16 v[62:65], v[146:149], v[162:165], v[62:65]
	v_mfma_f32_16x16x32_bf16 v[58:61], v[154:157], v[162:165], v[58:61]
	v_mfma_f32_16x16x32_bf16 v[54:57], v[146:149], v[174:177], v[54:57]
	v_mfma_f32_16x16x32_bf16 v[50:53], v[154:157], v[174:177], v[50:53]
	v_mfma_f32_16x16x32_bf16 v[46:49], v[146:149], v[182:185], v[46:49]
	v_mfma_f32_16x16x32_bf16 v[42:45], v[154:157], v[182:185], v[42:45]
	v_mfma_f32_16x16x32_bf16 v[38:41], v[146:149], v[190:193], v[38:41]
	v_mfma_f32_16x16x32_bf16 v[34:37], v[154:157], v[190:193], v[34:37]
	v_mfma_f32_16x16x32_bf16 v[62:65], v[150:153], v[166:169], v[62:65]
	v_mfma_f32_16x16x32_bf16 v[58:61], v[158:161], v[166:169], v[58:61]
	v_mfma_f32_16x16x32_bf16 v[54:57], v[150:153], v[178:181], v[54:57]
	v_mfma_f32_16x16x32_bf16 v[50:53], v[158:161], v[178:181], v[50:53]
	v_mfma_f32_16x16x32_bf16 v[46:49], v[150:153], v[186:189], v[46:49]
	v_mfma_f32_16x16x32_bf16 v[42:45], v[158:161], v[186:189], v[42:45]
	v_mfma_f32_16x16x32_bf16 v[38:41], v[150:153], v[194:197], v[38:41]
	v_mfma_f32_16x16x32_bf16 v[34:37], v[158:161], v[194:197], v[34:37]
	s_barrier
	v_add_u32_e32 v148, s50, v141
	v_lshl_add_u64 v[146:147], v[226:227], 0, s[12:13]
	v_readfirstlane_b32 s30, v148
	v_add_u32_e32 v148, 0x2000, v148
	s_mov_b32 m0, s30
	v_readfirstlane_b32 s30, v148
	global_load_lds_dwordx4 v[146:147], off
	v_lshl_add_u64 v[146:147], v[228:229], 0, s[12:13]
	s_mov_b32 m0, s30
	s_nop 0
	global_load_lds_dwordx4 v[146:147], off
	s_waitcnt vmcnt(10)
	s_barrier
	v_mfma_f32_16x16x32_bf16 v[30:33], v[198:201], v[162:165], v[30:33]
	v_mfma_f32_16x16x32_bf16 v[26:29], v[206:209], v[162:165], v[26:29]
	v_mfma_f32_16x16x32_bf16 v[22:25], v[198:201], v[174:177], v[22:25]
	v_mfma_f32_16x16x32_bf16 v[18:21], v[206:209], v[174:177], v[18:21]
	v_mfma_f32_16x16x32_bf16 v[14:17], v[198:201], v[182:185], v[14:17]
	v_mfma_f32_16x16x32_bf16 v[10:13], v[206:209], v[182:185], v[10:13]
	v_mfma_f32_16x16x32_bf16 v[6:9], v[198:201], v[190:193], v[6:9]
	v_mfma_f32_16x16x32_bf16 v[2:5], v[206:209], v[190:193], v[2:5]
	v_mfma_f32_16x16x32_bf16 v[30:33], v[202:205], v[166:169], v[30:33]
	v_mfma_f32_16x16x32_bf16 v[26:29], v[210:213], v[166:169], v[26:29]
	v_mfma_f32_16x16x32_bf16 v[22:25], v[202:205], v[178:181], v[22:25]
	v_mfma_f32_16x16x32_bf16 v[18:21], v[210:213], v[178:181], v[18:21]
	v_mfma_f32_16x16x32_bf16 v[14:17], v[202:205], v[186:189], v[14:17]
	v_mfma_f32_16x16x32_bf16 v[10:13], v[210:213], v[186:189], v[10:13]
	v_mfma_f32_16x16x32_bf16 v[6:9], v[202:205], v[194:197], v[6:9]
	v_mfma_f32_16x16x32_bf16 v[2:5], v[210:213], v[194:197], v[2:5]
	s_add_i32 s17, s17, 2
	s_cmp_lt_u32 s17, 4
	s_barrier
	s_cbranch_scc1 .LBB0_709
	v_lshl_add_u64 v[198:199], s[20:21], 0, v[130:131]
	v_readfirstlane_b32 s17, v144
	v_lshl_add_u64 v[198:199], v[198:199], 0, s[6:7]
	s_mov_b32 m0, s17
	v_lshl_add_u64 v[132:133], s[20:21], 0, v[132:133]
	v_readfirstlane_b32 s17, v145
	ds_read_b128 v[146:149], v143
	ds_read_b128 v[150:153], v143 offset:1024
	ds_read_b128 v[154:157], v143 offset:2048
	ds_read_b128 v[158:161], v143 offset:3072
	ds_read_b128 v[162:165], v138
	ds_read_b128 v[166:169], v138 offset:1024
	ds_read_b128 v[174:177], v137
	ds_read_b128 v[178:181], v137 offset:1024
	ds_read_b128 v[182:185], v136
	ds_read_b128 v[186:189], v136 offset:1024
	ds_read_b128 v[190:193], v135
	ds_read_b128 v[194:197], v135 offset:1024
	global_load_lds_dwordx4 v[198:199], off
	v_lshl_add_u64 v[132:133], v[132:133], 0, s[6:7]
	s_mov_b32 m0, s17
	s_nop 0
	global_load_lds_dwordx4 v[132:133], off
	s_waitcnt vmcnt(10)
	s_barrier
	s_waitcnt lgkmcnt(0)
	s_waitcnt lgkmcnt(0)
	v_mfma_f32_16x16x32_bf16 v[126:129], v[146:149], v[162:165], v[126:129]
	v_mfma_f32_16x16x32_bf16 v[122:125], v[154:157], v[162:165], v[122:125]
	v_mfma_f32_16x16x32_bf16 v[110:113], v[146:149], v[182:185], v[110:113]
	v_mfma_f32_16x16x32_bf16 v[106:109], v[154:157], v[182:185], v[106:109]
	v_mfma_f32_16x16x32_bf16 v[126:129], v[150:153], v[166:169], v[126:129]
	v_mfma_f32_16x16x32_bf16 v[122:125], v[158:161], v[166:169], v[122:125]
	v_mfma_f32_16x16x32_bf16 v[118:121], v[146:149], v[174:177], v[118:121]
	v_mfma_f32_16x16x32_bf16 v[114:117], v[154:157], v[174:177], v[114:117]
	v_mfma_f32_16x16x32_bf16 v[110:113], v[150:153], v[186:189], v[110:113]
	v_mfma_f32_16x16x32_bf16 v[106:109], v[158:161], v[186:189], v[106:109]
	v_mfma_f32_16x16x32_bf16 v[102:105], v[146:149], v[190:193], v[102:105]
	v_mfma_f32_16x16x32_bf16 v[98:101], v[154:157], v[190:193], v[98:101]
	v_mfma_f32_16x16x32_bf16 v[198:201], v[150:153], v[178:181], v[118:121]
	v_mfma_f32_16x16x32_bf16 v[202:205], v[158:161], v[178:181], v[114:117]
	v_mfma_f32_16x16x32_bf16 v[206:209], v[150:153], v[194:197], v[102:105]
	v_mfma_f32_16x16x32_bf16 v[210:213], v[158:161], v[194:197], v[98:101]
	s_barrier
	s_nop 1
	ds_read_b128 v[98:101], v142
	ds_read_b128 v[102:105], v142 offset:1024
	ds_read_b128 v[114:117], v142 offset:2048
	ds_read_b128 v[118:121], v142 offset:3072
	s_waitcnt vmcnt(8)
	s_barrier
; #define WAIT_V(n) asm volatile("s_waitcnt vmcnt(" #n ")" ::: "memory")
; #define WAIT_L(n) asm volatile("s_waitcnt lgkmcnt(" #n ")" ::: "memory")
; #define BAR __builtin_amdgcn_s_barrier()
; #define LDA(dst, b, h) for (int m = 0; m < 4; ++m) for (int k = 0; k < 2; ++k) \
;     dst[m][k] = *reinterpret_cast<const bf16x8*>((char*)SA(b, h) + lds_byte(wr * 64 + m * 16 + fr, k * 32 + fq * 8))
; #define LDB(dst, b, h) for (int n = 0; n < 2; ++n) for (int k = 0; k < 2; ++k) \
;     dst[n][k] = *reinterpret_cast<const bf16x8*>((char*)SB(b, h) + lds_byte(wc * 32 + n * 16 + fr, k * 32 + fq * 8))
; #define MMA(ai, bj, At_, Bt_) do { __builtin_amdgcn_s_setprio(1); \
;     for (int m = 0; m < 4; ++m) for (int n = 0; n < 2; ++n) for (int k = 0; k < 2; ++k) \
;       acc[ai][bj][m][n] = __builtin_amdgcn_mfma_f32_16x16x32_bf16(At_[m][k], Bt_[n][k], acc[ai][bj][m][n], 0, 0, 0); \
;     __builtin_amdgcn_s_setprio(0); } while (0)
; template <int K, int LD = K>
; __device__ __forceinline__ void gemm_main(const GAS bf16* A, const GAS bf16* Bt, int brow, int bcol, f32x4 (&acc)[2][2][4][2]) {
;     ...
;     LDB(B1, 0, 1); BAR; WAIT_L(0); MMA(0, 1, At, B1); BAR;
;     LDA(At, 0, 1); WAIT_V(4); BAR; WAIT_L(0); MMA(1, 0, At, B0); MMA(1, 1, At, B1); BAR; }
;   { LDB(B0, 1, 0); LDA(At, 1, 0); WAIT_V(2); BAR; WAIT_L(0); MMA(0, 0, At, B0); BAR;
;     LDB(B1, 1, 1); WAIT_V(0); BAR; WAIT_L(0); MMA(0, 1, At, B1); BAR;
	s_waitcnt lgkmcnt(0)
	s_waitcnt lgkmcnt(0)
	v_mfma_f32_16x16x32_bf16 v[94:97], v[98:101], v[162:165], v[94:97]
	v_mfma_f32_16x16x32_bf16 v[90:93], v[114:117], v[162:165], v[90:93]
	v_mfma_f32_16x16x32_bf16 v[70:73], v[98:101], v[190:193], v[70:73]
	v_mfma_f32_16x16x32_bf16 v[66:69], v[114:117], v[190:193], v[66:69]
	v_mfma_f32_16x16x32_bf16 v[94:97], v[102:105], v[166:169], v[94:97]
	v_mfma_f32_16x16x32_bf16 v[90:93], v[118:121], v[166:169], v[90:93]
	v_mfma_f32_16x16x32_bf16 v[86:89], v[98:101], v[174:177], v[86:89]
	v_mfma_f32_16x16x32_bf16 v[82:85], v[114:117], v[174:177], v[82:85]
	v_mfma_f32_16x16x32_bf16 v[78:81], v[98:101], v[182:185], v[78:81]
	v_mfma_f32_16x16x32_bf16 v[74:77], v[114:117], v[182:185], v[74:77]
	v_mfma_f32_16x16x32_bf16 v[70:73], v[102:105], v[194:197], v[70:73]
	v_mfma_f32_16x16x32_bf16 v[66:69], v[118:121], v[194:197], v[66:69]
	v_mfma_f32_16x16x32_bf16 v[142:145], v[102:105], v[178:181], v[86:89]
	v_mfma_f32_16x16x32_bf16 v[162:165], v[118:121], v[178:181], v[82:85]
	v_mfma_f32_16x16x32_bf16 v[166:169], v[102:105], v[186:189], v[78:81]
	v_mfma_f32_16x16x32_bf16 v[174:177], v[118:121], v[186:189], v[74:77]
	s_barrier
	s_nop 0
	ds_read_b128 v[74:77], v138 offset:16384
	ds_read_b128 v[78:81], v138 offset:17408
	ds_read_b128 v[82:85], v137 offset:16384
	ds_read_b128 v[86:89], v137 offset:17408
	ds_read_b128 v[178:181], v136 offset:16384
	ds_read_b128 v[182:185], v136 offset:17408
	ds_read_b128 v[186:189], v135 offset:16384
	ds_read_b128 v[190:193], v135 offset:17408
	s_waitcnt vmcnt(4)
	s_barrier
	s_waitcnt lgkmcnt(0)
	s_waitcnt lgkmcnt(0)
	v_mfma_f32_16x16x32_bf16 v[62:65], v[146:149], v[74:77], v[62:65]
	v_mfma_f32_16x16x32_bf16 v[58:61], v[154:157], v[74:77], v[58:61]
	v_mfma_f32_16x16x32_bf16 v[54:57], v[146:149], v[82:85], v[54:57]
	v_mfma_f32_16x16x32_bf16 v[50:53], v[154:157], v[82:85], v[50:53]
	v_mfma_f32_16x16x32_bf16 v[38:41], v[146:149], v[186:189], v[38:41]
	v_mfma_f32_16x16x32_bf16 v[34:37], v[154:157], v[186:189], v[34:37]
	v_mfma_f32_16x16x32_bf16 v[62:65], v[150:153], v[78:81], v[62:65]
	v_mfma_f32_16x16x32_bf16 v[58:61], v[158:161], v[78:81], v[58:61]
	v_mfma_f32_16x16x32_bf16 v[54:57], v[150:153], v[86:89], v[54:57]
	v_mfma_f32_16x16x32_bf16 v[50:53], v[158:161], v[86:89], v[50:53]
	v_mfma_f32_16x16x32_bf16 v[46:49], v[146:149], v[178:181], v[46:49]
	v_mfma_f32_16x16x32_bf16 v[42:45], v[154:157], v[178:181], v[42:45]
	v_mfma_f32_16x16x32_bf16 v[38:41], v[150:153], v[190:193], v[38:41]
	v_mfma_f32_16x16x32_bf16 v[34:37], v[158:161], v[190:193], v[34:37]
	v_mfma_f32_16x16x32_bf16 v[194:197], v[150:153], v[182:185], v[46:49]
	v_mfma_f32_16x16x32_bf16 v[214:217], v[158:161], v[182:185], v[42:45]
	v_mfma_f32_16x16x32_bf16 v[22:25], v[98:101], v[82:85], v[22:25]
	v_mfma_f32_16x16x32_bf16 v[18:21], v[114:117], v[82:85], v[18:21]
	v_mfma_f32_16x16x32_bf16 v[14:17], v[98:101], v[178:181], v[14:17]
	v_mfma_f32_16x16x32_bf16 v[10:13], v[114:117], v[178:181], v[10:13]
	v_mfma_f32_16x16x32_bf16 v[30:33], v[98:101], v[74:77], v[30:33]
	v_mfma_f32_16x16x32_bf16 v[26:29], v[114:117], v[74:77], v[26:29]
	v_mfma_f32_16x16x32_bf16 v[22:25], v[102:105], v[86:89], v[22:25]
	v_mfma_f32_16x16x32_bf16 v[18:21], v[118:121], v[86:89], v[18:21]
	v_mfma_f32_16x16x32_bf16 v[14:17], v[102:105], v[182:185], v[14:17]
	v_mfma_f32_16x16x32_bf16 v[10:13], v[118:121], v[182:185], v[10:13]
	v_mfma_f32_16x16x32_bf16 v[6:9], v[98:101], v[186:189], v[6:9]
	v_mfma_f32_16x16x32_bf16 v[2:5], v[114:117], v[186:189], v[2:5]
	v_mfma_f32_16x16x32_bf16 v[146:149], v[102:105], v[78:81], v[30:33]
	v_mfma_f32_16x16x32_bf16 v[150:153], v[118:121], v[78:81], v[26:29]
	v_mfma_f32_16x16x32_bf16 v[154:157], v[102:105], v[190:193], v[6:9]
	v_mfma_f32_16x16x32_bf16 v[158:161], v[118:121], v[190:193], v[2:5]
	s_barrier
	s_nop 1
	ds_read_b128 v[2:5], v140
	ds_read_b128 v[6:9], v140 offset:1024
	ds_read_b128 v[178:181], v140 offset:2048
	ds_read_b128 v[182:185], v140 offset:3072
	ds_read_b128 v[26:29], v138 offset:32768
	ds_read_b128 v[30:33], v138 offset:33792
	ds_read_b128 v[42:45], v137 offset:32768
	ds_read_b128 v[46:49], v137 offset:33792
	ds_read_b128 v[186:189], v136 offset:32768
	ds_read_b128 v[190:193], v136 offset:33792
	ds_read_b128 v[218:221], v135 offset:32768
	ds_read_b128 v[222:225], v135 offset:33792
	s_waitcnt vmcnt(2)
	s_barrier
; #define WAIT_V(n) asm volatile("s_waitcnt vmcnt(" #n ")" ::: "memory")
; #define WAIT_L(n) asm volatile("s_waitcnt lgkmcnt(" #n ")" ::: "memory")
; #define BAR __builtin_amdgcn_s_barrier()
; #define LDA(dst, b, h) for (int m = 0; m < 4; ++m) for (int k = 0; k < 2; ++k) \
;     dst[m][k] = *reinterpret_cast<const bf16x8*>((char*)SA(b, h) + lds_byte(wr * 64 + m * 16 + fr, k * 32 + fq * 8))
; #define LDB(dst, b, h) for (int n = 0; n < 2; ++n) for (int k = 0; k < 2; ++k) \
;     dst[n][k] = *reinterpret_cast<const bf16x8*>((char*)SB(b, h) + lds_byte(wc * 32 + n * 16 + fr, k * 32 + fq * 8))
; #define MMA(ai, bj, At_, Bt_) do { __builtin_amdgcn_s_setprio(1); \
;     for (int m = 0; m < 4; ++m) for (int n = 0; n < 2; ++n) for (int k = 0; k < 2; ++k) \
;       acc[ai][bj][m][n] = __builtin_amdgcn_mfma_f32_16x16x32_bf16(At_[m][k], Bt_[n][k], acc[ai][bj][m][n], 0, 0, 0); \
;     __builtin_amdgcn_s_setprio(0); } while (0)
; template <int K, int LD = K>
; __device__ __forceinline__ void gemm_main(const GAS bf16* A, const GAS bf16* Bt, int brow, int bcol, f32x4 (&acc)[2][2][4][2]) {
;     ...
;     LDB(B1, 1, 1); WAIT_V(0); BAR; WAIT_L(0); MMA(0, 1, At, B1); BAR;
;     LDA(At, 1, 1); BAR; WAIT_L(0); MMA(1, 0, At, B0); MMA(1, 1, At, B1); BAR; }
;   if (wr == 0) BAR;
	s_waitcnt lgkmcnt(0)
	s_waitcnt lgkmcnt(0)
	v_mfma_f32_16x16x32_bf16 v[74:77], v[2:5], v[26:29], v[126:129]
	v_mfma_f32_16x16x32_bf16 v[118:121], v[6:9], v[30:33], v[74:77]
	v_mfma_f32_16x16x32_bf16 v[74:77], v[178:181], v[26:29], v[122:125]
	v_mfma_f32_16x16x32_bf16 v[114:117], v[182:185], v[30:33], v[74:77]
	v_mfma_f32_16x16x32_bf16 v[74:77], v[2:5], v[42:45], v[198:201]
	v_mfma_f32_16x16x32_bf16 v[102:105], v[6:9], v[46:49], v[74:77]
	v_mfma_f32_16x16x32_bf16 v[74:77], v[178:181], v[42:45], v[202:205]
	v_mfma_f32_16x16x32_bf16 v[98:101], v[182:185], v[46:49], v[74:77]
	v_mfma_f32_16x16x32_bf16 v[74:77], v[2:5], v[186:189], v[110:113]
	v_mfma_f32_16x16x32_bf16 v[86:89], v[6:9], v[190:193], v[74:77]
	v_mfma_f32_16x16x32_bf16 v[74:77], v[178:181], v[186:189], v[106:109]
	v_mfma_f32_16x16x32_bf16 v[82:85], v[182:185], v[190:193], v[74:77]
	v_mfma_f32_16x16x32_bf16 v[74:77], v[2:5], v[218:221], v[206:209]
	v_mfma_f32_16x16x32_bf16 v[78:81], v[6:9], v[222:225], v[74:77]
	v_mfma_f32_16x16x32_bf16 v[74:77], v[178:181], v[218:221], v[210:213]
	v_mfma_f32_16x16x32_bf16 v[74:77], v[182:185], v[222:225], v[74:77]
	s_barrier
	ds_read_b128 v[198:201], v139
	ds_read_b128 v[202:205], v139 offset:1024
	ds_read_b128 v[206:209], v139 offset:2048
	ds_read_b128 v[210:213], v139 offset:3072
	s_waitcnt vmcnt(0)
	s_barrier
	s_waitcnt lgkmcnt(0)
	s_waitcnt lgkmcnt(0)
	v_mfma_f32_16x16x32_bf16 v[94:97], v[198:201], v[26:29], v[94:97]
	v_mfma_f32_16x16x32_bf16 v[26:29], v[206:209], v[26:29], v[90:93]
	v_mfma_f32_16x16x32_bf16 v[122:125], v[210:213], v[30:33], v[26:29]
	v_mfma_f32_16x16x32_bf16 v[26:29], v[198:201], v[42:45], v[142:145]
	v_mfma_f32_16x16x32_bf16 v[110:113], v[202:205], v[46:49], v[26:29]
	v_mfma_f32_16x16x32_bf16 v[26:29], v[206:209], v[42:45], v[162:165]
	v_mfma_f32_16x16x32_bf16 v[106:109], v[210:213], v[46:49], v[26:29]
	v_mfma_f32_16x16x32_bf16 v[26:29], v[198:201], v[186:189], v[166:169]
	v_mfma_f32_16x16x32_bf16 v[126:129], v[202:205], v[30:33], v[94:97]
	v_mfma_f32_16x16x32_bf16 v[94:97], v[202:205], v[190:193], v[26:29]
	v_mfma_f32_16x16x32_bf16 v[26:29], v[206:209], v[186:189], v[174:177]
	v_mfma_f32_16x16x32_bf16 v[90:93], v[210:213], v[190:193], v[26:29]
	v_mfma_f32_16x16x32_bf16 v[26:29], v[198:201], v[218:221], v[70:73]
	v_mfma_f32_16x16x32_bf16 v[70:73], v[202:205], v[222:225], v[26:29]
	v_mfma_f32_16x16x32_bf16 v[26:29], v[206:209], v[218:221], v[66:69]
	v_mfma_f32_16x16x32_bf16 v[66:69], v[210:213], v[222:225], v[26:29]
	s_barrier
	ds_read_b128 v[140:143], v138 offset:49152
	ds_read_b128 v[162:165], v138 offset:50176
	ds_read_b128 v[166:169], v137 offset:49152
	ds_read_b128 v[174:177], v137 offset:50176
	ds_read_b128 v[186:189], v136 offset:49152
	ds_read_b128 v[136:139], v136 offset:50176
	ds_read_b128 v[190:193], v135 offset:49152
	ds_read_b128 v[218:221], v135 offset:50176
	s_barrier
	s_waitcnt lgkmcnt(0)
	s_waitcnt lgkmcnt(0)
	v_mfma_f32_16x16x32_bf16 v[26:29], v[2:5], v[140:143], v[62:65]
	v_mfma_f32_16x16x32_bf16 v[62:65], v[6:9], v[162:165], v[26:29]
	v_mfma_f32_16x16x32_bf16 v[26:29], v[178:181], v[140:143], v[58:61]
	v_mfma_f32_16x16x32_bf16 v[58:61], v[182:185], v[162:165], v[26:29]
	v_mfma_f32_16x16x32_bf16 v[26:29], v[2:5], v[166:169], v[54:57]
	v_mfma_f32_16x16x32_bf16 v[46:49], v[6:9], v[174:177], v[26:29]
	v_mfma_f32_16x16x32_bf16 v[26:29], v[178:181], v[166:169], v[50:53]
	v_mfma_f32_16x16x32_bf16 v[42:45], v[182:185], v[174:177], v[26:29]
	v_mfma_f32_16x16x32_bf16 v[26:29], v[2:5], v[186:189], v[194:197]
	v_mfma_f32_16x16x32_bf16 v[2:5], v[2:5], v[190:193], v[38:41]
	v_mfma_f32_16x16x32_bf16 v[30:33], v[6:9], v[136:139], v[26:29]
	v_mfma_f32_16x16x32_bf16 v[26:29], v[178:181], v[186:189], v[214:217]
	v_mfma_f32_16x16x32_bf16 v[6:9], v[6:9], v[218:221], v[2:5]
	v_mfma_f32_16x16x32_bf16 v[2:5], v[178:181], v[190:193], v[34:37]
	v_mfma_f32_16x16x32_bf16 v[26:29], v[182:185], v[136:139], v[26:29]
	v_mfma_f32_16x16x32_bf16 v[2:5], v[182:185], v[218:221], v[2:5]
	v_mfma_f32_16x16x32_bf16 v[34:37], v[198:201], v[140:143], v[146:149]
	v_mfma_f32_16x16x32_bf16 v[54:57], v[202:205], v[162:165], v[34:37]
	v_mfma_f32_16x16x32_bf16 v[34:37], v[206:209], v[140:143], v[150:153]
	v_mfma_f32_16x16x32_bf16 v[18:21], v[206:209], v[166:169], v[18:21]
	v_mfma_f32_16x16x32_bf16 v[10:13], v[206:209], v[186:189], v[10:13]
	v_mfma_f32_16x16x32_bf16 v[50:53], v[210:213], v[162:165], v[34:37]
	v_mfma_f32_16x16x32_bf16 v[22:25], v[198:201], v[166:169], v[22:25]
	v_mfma_f32_16x16x32_bf16 v[34:37], v[210:213], v[174:177], v[18:21]
	v_mfma_f32_16x16x32_bf16 v[14:17], v[198:201], v[186:189], v[14:17]
	v_mfma_f32_16x16x32_bf16 v[18:21], v[210:213], v[136:139], v[10:13]
	v_mfma_f32_16x16x32_bf16 v[10:13], v[198:201], v[190:193], v[154:157]
	v_mfma_f32_16x16x32_bf16 v[38:41], v[202:205], v[174:177], v[22:25]
	v_mfma_f32_16x16x32_bf16 v[22:25], v[202:205], v[136:139], v[14:17]
	v_mfma_f32_16x16x32_bf16 v[14:17], v[202:205], v[218:221], v[10:13]
	v_mfma_f32_16x16x32_bf16 v[10:13], v[206:209], v[190:193], v[158:161]
	v_mfma_f32_16x16x32_bf16 v[10:13], v[210:213], v[218:221], v[10:13]
	v_cmp_gt_u32_e32 vcc, s51, v134
	s_barrier
	s_and_saveexec_b64 s[20:21], vcc
	s_cbranch_execz .LBB0_712
	s_barrier

; #define STAGE(P, GP, ktrel) do { const GAS char* _g = (GP) + (ktrel) * (BK * 2); \
;     __builtin_amdgcn_global_load_lds((const GAS unsigned*)(_g + so0), (unsigned*)((char*)(P) + tid_ * 16), 16, 0, 0); \
;     __builtin_amdgcn_global_load_lds((const GAS unsigned*)(_g + so1), (unsigned*)((char*)(P) + tid_ * 16 + 8192), 16, 0, 0); } while (0)
; #define WAIT_V(n) asm volatile("s_waitcnt vmcnt(" #n ")" ::: "memory")
; #define WAIT_L(n) asm volatile("s_waitcnt lgkmcnt(" #n ")" ::: "memory")
; #define BAR __builtin_amdgcn_s_barrier()
; #define SCHED __builtin_amdgcn_sched_barrier(0)
; #define LDA(dst, b, h) for (int m = 0; m < 4; ++m) for (int k = 0; k < 2; ++k) \
;     dst[m][k] = *reinterpret_cast<const bf16x8*>((char*)SA(b, h) + lds_byte(wr * 64 + m * 16 + fr, k * 32 + fq * 8))
; #define LDB(dst, b, h) for (int n = 0; n < 2; ++n) for (int k = 0; k < 2; ++k) \
;     dst[n][k] = *reinterpret_cast<const bf16x8*>((char*)SB(b, h) + lds_byte(wc * 32 + n * 16 + fr, k * 32 + fq * 8))
; #define MMA(ai, bj, At_, Bt_) do { __builtin_amdgcn_s_setprio(1); \
;     for (int m = 0; m < 4; ++m) for (int n = 0; n < 2; ++n) for (int k = 0; k < 2; ++k) \
;       acc[ai][bj][m][n] = __builtin_amdgcn_mfma_f32_16x16x32_bf16(At_[m][k], Bt_[n][k], acc[ai][bj][m][n], 0, 0, 0); \
;     __builtin_amdgcn_s_setprio(0); } while (0)
; template <int K, int LD = K>
; __device__ __forceinline__ void gemm_main(const GAS bf16* A, const GAS bf16* Bt, int brow, int bcol, f32x4 (&acc)[2][2][4][2]) {
;     ...
;     LDB(B0, 0, 0); SCHED; LDA(At, 0, 0); STAGE(SA(1, 1), pA1, 1);
;     WAIT_L(8); BAR; WAIT_L(0); MMA(0, 0, At, B0); BAR; SCHED;
;     LDB(B1, 0, 1); STAGE(SB(0, 0), pB0, 2);
;     BAR; WAIT_L(0); MMA(0, 1, At, B1); BAR;
;     LDA(At, 0, 1); STAGE(SA(0, 0), pA0, 2);
;     BAR; WAIT_L(0); MMA(1, 0, At, B0); BAR; SCHED;
;     STAGE(SB(0, 1), pB1, 2);
;     WAIT_V(6); BAR; MMA(1, 1, At, B1); BAR;
.LBB0_884:
	ds_read_b128 v[160:163], v145
	ds_read_b128 v[164:167], v145 offset:1024
	ds_read_b128 v[174:177], v145 offset:2048
	ds_read_b128 v[178:181], v145 offset:3072
	v_lshl_add_u64 v[168:169], s[12:13], 0, v[130:131]
	v_readfirstlane_b32 s22, v144
	v_lshl_add_u64 v[214:215], v[168:169], 0, s[6:7]
	s_mov_b32 m0, s22
	v_lshl_add_u64 v[230:231], s[12:13], 0, v[132:133]
	v_readfirstlane_b32 s22, v143
	ds_read_b128 v[182:185], v139
	ds_read_b128 v[186:189], v139 offset:1024
	ds_read_b128 v[190:193], v138
	ds_read_b128 v[194:197], v138 offset:1024
	ds_read_b128 v[198:201], v137
	ds_read_b128 v[202:205], v137 offset:1024
	ds_read_b128 v[206:209], v136
	ds_read_b128 v[210:213], v136 offset:1024
	global_load_lds_dwordx4 v[214:215], off
	v_lshl_add_u64 v[214:215], v[230:231], 0, s[6:7]
	s_mov_b32 m0, s22
	s_nop 0
	global_load_lds_dwordx4 v[214:215], off
	s_waitcnt lgkmcnt(8)
	s_waitcnt vmcnt(10)
	s_barrier
	s_waitcnt lgkmcnt(0)
	s_waitcnt lgkmcnt(0)
	v_mfma_f32_16x16x32_bf16 v[126:129], v[160:163], v[182:185], v[126:129]
	v_mfma_f32_16x16x32_bf16 v[122:125], v[174:177], v[182:185], v[122:125]
	v_mfma_f32_16x16x32_bf16 v[118:121], v[160:163], v[190:193], v[118:121]
	v_mfma_f32_16x16x32_bf16 v[114:117], v[174:177], v[190:193], v[114:117]
	v_mfma_f32_16x16x32_bf16 v[110:113], v[160:163], v[198:201], v[110:113]
	v_mfma_f32_16x16x32_bf16 v[106:109], v[174:177], v[198:201], v[106:109]
	v_mfma_f32_16x16x32_bf16 v[102:105], v[160:163], v[206:209], v[102:105]
	v_mfma_f32_16x16x32_bf16 v[98:101], v[174:177], v[206:209], v[98:101]
	v_mfma_f32_16x16x32_bf16 v[126:129], v[164:167], v[186:189], v[126:129]
	v_mfma_f32_16x16x32_bf16 v[122:125], v[178:181], v[186:189], v[122:125]
	v_mfma_f32_16x16x32_bf16 v[118:121], v[164:167], v[194:197], v[118:121]
	v_mfma_f32_16x16x32_bf16 v[114:117], v[178:181], v[194:197], v[114:117]
	v_mfma_f32_16x16x32_bf16 v[110:113], v[164:167], v[202:205], v[110:113]
	v_mfma_f32_16x16x32_bf16 v[106:109], v[178:181], v[202:205], v[106:109]
	v_mfma_f32_16x16x32_bf16 v[102:105], v[164:167], v[210:213], v[102:105]
	v_mfma_f32_16x16x32_bf16 v[98:101], v[178:181], v[210:213], v[98:101]
	s_barrier
	v_lshl_add_u64 v[232:233], s[20:21], 0, v[130:131]
	v_readfirstlane_b32 s22, v152
	v_lshl_add_u64 v[234:235], v[232:233], 0, s[8:9]
	s_mov_b32 m0, s22
	ds_read_b128 v[214:217], v142
	ds_read_b128 v[218:221], v142 offset:1024
	ds_read_b128 v[222:225], v142 offset:2048
	ds_read_b128 v[226:229], v142 offset:3072
	global_load_lds_dwordx4 v[234:235], off
	v_lshl_add_u64 v[234:235], s[20:21], 0, v[132:133]
	v_readfirstlane_b32 s22, v153
	v_lshl_add_u64 v[236:237], v[234:235], 0, s[8:9]
	s_mov_b32 m0, s22
	s_add_u32 s20, s20, 0x100
	global_load_lds_dwordx4 v[236:237], off
	s_waitcnt vmcnt(10)
	s_barrier
	s_waitcnt lgkmcnt(0)
	s_addc_u32 s21, s21, 0
	s_waitcnt lgkmcnt(0)
	v_mfma_f32_16x16x32_bf16 v[94:97], v[214:217], v[182:185], v[94:97]
	v_mfma_f32_16x16x32_bf16 v[90:93], v[222:225], v[182:185], v[90:93]
	v_mfma_f32_16x16x32_bf16 v[86:89], v[214:217], v[190:193], v[86:89]
	v_mfma_f32_16x16x32_bf16 v[82:85], v[222:225], v[190:193], v[82:85]
	v_mfma_f32_16x16x32_bf16 v[78:81], v[214:217], v[198:201], v[78:81]
	v_mfma_f32_16x16x32_bf16 v[74:77], v[222:225], v[198:201], v[74:77]
	v_mfma_f32_16x16x32_bf16 v[70:73], v[214:217], v[206:209], v[70:73]
	v_mfma_f32_16x16x32_bf16 v[66:69], v[222:225], v[206:209], v[66:69]
	v_mfma_f32_16x16x32_bf16 v[94:97], v[218:221], v[186:189], v[94:97]
	v_mfma_f32_16x16x32_bf16 v[90:93], v[226:229], v[186:189], v[90:93]
	v_mfma_f32_16x16x32_bf16 v[86:89], v[218:221], v[194:197], v[86:89]
	v_mfma_f32_16x16x32_bf16 v[82:85], v[226:229], v[194:197], v[82:85]
	v_mfma_f32_16x16x32_bf16 v[78:81], v[218:221], v[202:205], v[78:81]
	v_mfma_f32_16x16x32_bf16 v[74:77], v[226:229], v[202:205], v[74:77]
	v_mfma_f32_16x16x32_bf16 v[70:73], v[218:221], v[210:213], v[70:73]
	v_mfma_f32_16x16x32_bf16 v[66:69], v[226:229], v[210:213], v[66:69]
	v_lshl_add_u64 v[236:237], s[18:19], 0, v[130:131]
	v_readfirstlane_b32 s22, v146
	v_lshl_add_u64 v[238:239], v[236:237], 0, s[8:9]
	s_mov_b32 m0, s22
	s_barrier
	ds_read_b128 v[182:185], v139 offset:16384
	ds_read_b128 v[186:189], v139 offset:17408
	ds_read_b128 v[190:193], v138 offset:16384
	ds_read_b128 v[194:197], v138 offset:17408
	ds_read_b128 v[198:201], v137 offset:16384
	ds_read_b128 v[202:205], v137 offset:17408
	ds_read_b128 v[206:209], v136 offset:16384
	ds_read_b128 v[210:213], v136 offset:17408
	global_load_lds_dwordx4 v[238:239], off
	v_lshl_add_u64 v[238:239], s[18:19], 0, v[132:133]
	v_readfirstlane_b32 s22, v147
	v_lshl_add_u64 v[240:241], v[238:239], 0, s[8:9]
	s_mov_b32 m0, s22
	s_add_u32 s18, s18, 0x100
	global_load_lds_dwordx4 v[240:241], off
	s_barrier
	s_waitcnt lgkmcnt(0)
	s_addc_u32 s19, s19, 0
	s_waitcnt lgkmcnt(0)
	v_mfma_f32_16x16x32_bf16 v[62:65], v[160:163], v[182:185], v[62:65]
	v_mfma_f32_16x16x32_bf16 v[58:61], v[174:177], v[182:185], v[58:61]
	v_mfma_f32_16x16x32_bf16 v[54:57], v[160:163], v[190:193], v[54:57]
	v_mfma_f32_16x16x32_bf16 v[50:53], v[174:177], v[190:193], v[50:53]
	v_mfma_f32_16x16x32_bf16 v[46:49], v[160:163], v[198:201], v[46:49]
	v_mfma_f32_16x16x32_bf16 v[42:45], v[174:177], v[198:201], v[42:45]
	v_mfma_f32_16x16x32_bf16 v[38:41], v[160:163], v[206:209], v[38:41]
	v_mfma_f32_16x16x32_bf16 v[34:37], v[174:177], v[206:209], v[34:37]
	v_mfma_f32_16x16x32_bf16 v[62:65], v[164:167], v[186:189], v[62:65]
	v_mfma_f32_16x16x32_bf16 v[58:61], v[178:181], v[186:189], v[58:61]
	v_mfma_f32_16x16x32_bf16 v[54:57], v[164:167], v[194:197], v[54:57]
	v_mfma_f32_16x16x32_bf16 v[50:53], v[178:181], v[194:197], v[50:53]
	v_mfma_f32_16x16x32_bf16 v[46:49], v[164:167], v[202:205], v[46:49]
	v_mfma_f32_16x16x32_bf16 v[42:45], v[178:181], v[202:205], v[42:45]
	v_mfma_f32_16x16x32_bf16 v[38:41], v[164:167], v[210:213], v[38:41]
	v_mfma_f32_16x16x32_bf16 v[34:37], v[178:181], v[210:213], v[34:37]
	s_barrier
; #define STAGE(P, GP, ktrel) do { const GAS char* _g = (GP) + (ktrel) * (BK * 2); \
;     __builtin_amdgcn_global_load_lds((const GAS unsigned*)(_g + so0), (unsigned*)((char*)(P) + tid_ * 16), 16, 0, 0); \
;     __builtin_amdgcn_global_load_lds((const GAS unsigned*)(_g + so1), (unsigned*)((char*)(P) + tid_ * 16 + 8192), 16, 0, 0); } while (0)
; #define WAIT_V(n) asm volatile("s_waitcnt vmcnt(" #n ")" ::: "memory")
; #define WAIT_L(n) asm volatile("s_waitcnt lgkmcnt(" #n ")" ::: "memory")
; #define BAR __builtin_amdgcn_s_barrier()
; #define SCHED __builtin_amdgcn_sched_barrier(0)
; #define LDA(dst, b, h) for (int m = 0; m < 4; ++m) for (int k = 0; k < 2; ++k) \
;     dst[m][k] = *reinterpret_cast<const bf16x8*>((char*)SA(b, h) + lds_byte(wr * 64 + m * 16 + fr, k * 32 + fq * 8))
; #define LDB(dst, b, h) for (int n = 0; n < 2; ++n) for (int k = 0; k < 2; ++k) \
;     dst[n][k] = *reinterpret_cast<const bf16x8*>((char*)SB(b, h) + lds_byte(wc * 32 + n * 16 + fr, k * 32 + fq * 8))
; #define MMA(ai, bj, At_, Bt_) do { __builtin_amdgcn_s_setprio(1); \
;     for (int m = 0; m < 4; ++m) for (int n = 0; n < 2; ++n) for (int k = 0; k < 2; ++k) \
;       acc[ai][bj][m][n] = __builtin_amdgcn_mfma_f32_16x16x32_bf16(At_[m][k], Bt_[n][k], acc[ai][bj][m][n], 0, 0, 0); \
;     __builtin_amdgcn_s_setprio(0); } while (0)
; template <int K, int LD = K>
; __device__ __forceinline__ void gemm_main(const GAS bf16* A, const GAS bf16* Bt, int brow, int bcol, f32x4 (&acc)[2][2][4][2]) {
;     ...
;     WAIT_V(6); BAR; MMA(1, 1, At, B1); BAR;
;     LDB(B0, 1, 0); SCHED; LDA(At, 1, 0); STAGE(SA(0, 1), pA1, 2);
;     WAIT_L(8); BAR; WAIT_L(0); MMA(0, 0, At, B0); BAR; SCHED;
;     LDB(B1, 1, 1); STAGE(SB(1, 0), pB0, 3);
;     BAR; WAIT_L(0); MMA(0, 1, At, B1); BAR;
;     LDA(At, 1, 1); STAGE(SA(1, 0), pA0, 3);
;     BAR; WAIT_L(0); MMA(1, 0, At, B0); BAR; SCHED;
	v_lshl_add_u64 v[240:241], s[16:17], 0, v[130:131]
	v_readfirstlane_b32 s22, v154
	v_lshl_add_u64 v[160:161], v[240:241], 0, s[8:9]
	s_mov_b32 m0, s22
	v_lshl_add_u64 v[242:243], s[16:17], 0, v[132:133]
	v_readfirstlane_b32 s22, v155
	global_load_lds_dwordx4 v[160:161], off
	v_lshl_add_u64 v[160:161], v[242:243], 0, s[8:9]
	s_mov_b32 m0, s22
	s_add_u32 s16, s16, 0x100
	global_load_lds_dwordx4 v[160:161], off
	s_waitcnt vmcnt(10)
	s_addc_u32 s17, s17, 0
	s_barrier
	v_mfma_f32_16x16x32_bf16 v[30:33], v[214:217], v[182:185], v[30:33]
	v_mfma_f32_16x16x32_bf16 v[26:29], v[222:225], v[182:185], v[26:29]
	v_mfma_f32_16x16x32_bf16 v[22:25], v[214:217], v[190:193], v[22:25]
	v_mfma_f32_16x16x32_bf16 v[18:21], v[222:225], v[190:193], v[18:21]
	v_mfma_f32_16x16x32_bf16 v[14:17], v[214:217], v[198:201], v[14:17]
	v_mfma_f32_16x16x32_bf16 v[10:13], v[222:225], v[198:201], v[10:13]
	v_mfma_f32_16x16x32_bf16 v[6:9], v[214:217], v[206:209], v[6:9]
	v_mfma_f32_16x16x32_bf16 v[2:5], v[222:225], v[206:209], v[2:5]
	v_mfma_f32_16x16x32_bf16 v[30:33], v[218:221], v[186:189], v[30:33]
	v_mfma_f32_16x16x32_bf16 v[26:29], v[226:229], v[186:189], v[26:29]
	v_mfma_f32_16x16x32_bf16 v[22:25], v[218:221], v[194:197], v[22:25]
	v_mfma_f32_16x16x32_bf16 v[18:21], v[226:229], v[194:197], v[18:21]
	v_mfma_f32_16x16x32_bf16 v[14:17], v[218:221], v[202:205], v[14:17]
	v_mfma_f32_16x16x32_bf16 v[10:13], v[226:229], v[202:205], v[10:13]
	v_mfma_f32_16x16x32_bf16 v[6:9], v[218:221], v[210:213], v[6:9]
	v_mfma_f32_16x16x32_bf16 v[2:5], v[226:229], v[210:213], v[2:5]
	s_barrier
	ds_read_b128 v[160:163], v141
	ds_read_b128 v[164:167], v141 offset:1024
	ds_read_b128 v[174:177], v141 offset:2048
	ds_read_b128 v[178:181], v141 offset:3072
	v_readfirstlane_b32 s22, v148
	v_lshl_add_u64 v[168:169], v[168:169], 0, s[8:9]
	s_mov_b32 m0, s22
	v_readfirstlane_b32 s22, v149
	ds_read_b128 v[182:185], v139 offset:32768
	ds_read_b128 v[186:189], v139 offset:33792
	ds_read_b128 v[190:193], v138 offset:32768
	ds_read_b128 v[194:197], v138 offset:33792
	ds_read_b128 v[198:201], v137 offset:32768
	ds_read_b128 v[202:205], v137 offset:33792
	ds_read_b128 v[206:209], v136 offset:32768
	ds_read_b128 v[210:213], v136 offset:33792
	global_load_lds_dwordx4 v[168:169], off
	v_lshl_add_u64 v[168:169], v[230:231], 0, s[8:9]
	s_mov_b32 m0, s22
	s_add_u32 s12, s12, 0x100
	global_load_lds_dwordx4 v[168:169], off
	s_waitcnt lgkmcnt(8)
	s_waitcnt vmcnt(10)
	s_barrier
	s_waitcnt lgkmcnt(0)
	s_addc_u32 s13, s13, 0
	s_waitcnt lgkmcnt(0)
	v_mfma_f32_16x16x32_bf16 v[126:129], v[160:163], v[182:185], v[126:129]
	v_mfma_f32_16x16x32_bf16 v[122:125], v[174:177], v[182:185], v[122:125]
	v_mfma_f32_16x16x32_bf16 v[118:121], v[160:163], v[190:193], v[118:121]
	v_mfma_f32_16x16x32_bf16 v[114:117], v[174:177], v[190:193], v[114:117]
	v_mfma_f32_16x16x32_bf16 v[110:113], v[160:163], v[198:201], v[110:113]
	v_mfma_f32_16x16x32_bf16 v[106:109], v[174:177], v[198:201], v[106:109]
	v_mfma_f32_16x16x32_bf16 v[102:105], v[160:163], v[206:209], v[102:105]
	v_mfma_f32_16x16x32_bf16 v[98:101], v[174:177], v[206:209], v[98:101]
	v_mfma_f32_16x16x32_bf16 v[126:129], v[164:167], v[186:189], v[126:129]
	v_mfma_f32_16x16x32_bf16 v[122:125], v[178:181], v[186:189], v[122:125]
	v_mfma_f32_16x16x32_bf16 v[118:121], v[164:167], v[194:197], v[118:121]
	v_mfma_f32_16x16x32_bf16 v[114:117], v[178:181], v[194:197], v[114:117]
	v_mfma_f32_16x16x32_bf16 v[110:113], v[164:167], v[202:205], v[110:113]
	v_mfma_f32_16x16x32_bf16 v[106:109], v[178:181], v[202:205], v[106:109]
	v_mfma_f32_16x16x32_bf16 v[102:105], v[164:167], v[210:213], v[102:105]
	v_mfma_f32_16x16x32_bf16 v[98:101], v[178:181], v[210:213], v[98:101]
	s_barrier
	v_readfirstlane_b32 s22, v156
	v_lshl_add_u64 v[168:169], v[232:233], 0, s[10:11]
	s_mov_b32 m0, s22
	v_readfirstlane_b32 s22, v157
	ds_read_b128 v[214:217], v140
	ds_read_b128 v[218:221], v140 offset:1024
	ds_read_b128 v[222:225], v140 offset:2048
	ds_read_b128 v[226:229], v140 offset:3072
	global_load_lds_dwordx4 v[168:169], off
	v_lshl_add_u64 v[168:169], v[234:235], 0, s[10:11]
	s_mov_b32 m0, s22
	s_nop 0
	global_load_lds_dwordx4 v[168:169], off
	s_waitcnt vmcnt(10)
	s_barrier
	s_waitcnt lgkmcnt(0)
	s_waitcnt lgkmcnt(0)
	v_mfma_f32_16x16x32_bf16 v[94:97], v[214:217], v[182:185], v[94:97]
	v_mfma_f32_16x16x32_bf16 v[90:93], v[222:225], v[182:185], v[90:93]
	v_mfma_f32_16x16x32_bf16 v[86:89], v[214:217], v[190:193], v[86:89]
	v_mfma_f32_16x16x32_bf16 v[82:85], v[222:225], v[190:193], v[82:85]
	v_mfma_f32_16x16x32_bf16 v[78:81], v[214:217], v[198:201], v[78:81]
	v_mfma_f32_16x16x32_bf16 v[74:77], v[222:225], v[198:201], v[74:77]
	v_mfma_f32_16x16x32_bf16 v[70:73], v[214:217], v[206:209], v[70:73]
	v_mfma_f32_16x16x32_bf16 v[66:69], v[222:225], v[206:209], v[66:69]
	v_mfma_f32_16x16x32_bf16 v[94:97], v[218:221], v[186:189], v[94:97]
	v_mfma_f32_16x16x32_bf16 v[90:93], v[226:229], v[186:189], v[90:93]
	v_mfma_f32_16x16x32_bf16 v[86:89], v[218:221], v[194:197], v[86:89]
	v_mfma_f32_16x16x32_bf16 v[82:85], v[226:229], v[194:197], v[82:85]
	v_mfma_f32_16x16x32_bf16 v[78:81], v[218:221], v[202:205], v[78:81]
	v_mfma_f32_16x16x32_bf16 v[74:77], v[226:229], v[202:205], v[74:77]
	v_mfma_f32_16x16x32_bf16 v[70:73], v[218:221], v[210:213], v[70:73]
	v_mfma_f32_16x16x32_bf16 v[66:69], v[226:229], v[210:213], v[66:69]
	v_readfirstlane_b32 s22, v150
	v_lshl_add_u64 v[168:169], v[236:237], 0, s[10:11]
	s_mov_b32 m0, s22
	v_readfirstlane_b32 s22, v151
	s_barrier
; #define STAGE(P, GP, ktrel) do { const GAS char* _g = (GP) + (ktrel) * (BK * 2); \
;     __builtin_amdgcn_global_load_lds((const GAS unsigned*)(_g + so0), (unsigned*)((char*)(P) + tid_ * 16), 16, 0, 0); \
;     __builtin_amdgcn_global_load_lds((const GAS unsigned*)(_g + so1), (unsigned*)((char*)(P) + tid_ * 16 + 8192), 16, 0, 0); } while (0)
; #define WAIT_V(n) asm volatile("s_waitcnt vmcnt(" #n ")" ::: "memory")
; #define WAIT_L(n) asm volatile("s_waitcnt lgkmcnt(" #n ")" ::: "memory")
; #define BAR __builtin_amdgcn_s_barrier()
; #define SCHED __builtin_amdgcn_sched_barrier(0)
; #define LDA(dst, b, h) for (int m = 0; m < 4; ++m) for (int k = 0; k < 2; ++k) \
;     dst[m][k] = *reinterpret_cast<const bf16x8*>((char*)SA(b, h) + lds_byte(wr * 64 + m * 16 + fr, k * 32 + fq * 8))
; #define LDB(dst, b, h) for (int n = 0; n < 2; ++n) for (int k = 0; k < 2; ++k) \
;     dst[n][k] = *reinterpret_cast<const bf16x8*>((char*)SB(b, h) + lds_byte(wc * 32 + n * 16 + fr, k * 32 + fq * 8))
; #define MMA(ai, bj, At_, Bt_) do { __builtin_amdgcn_s_setprio(1); \
;     for (int m = 0; m < 4; ++m) for (int n = 0; n < 2; ++n) for (int k = 0; k < 2; ++k) \
;       acc[ai][bj][m][n] = __builtin_amdgcn_mfma_f32_16x16x32_bf16(At_[m][k], Bt_[n][k], acc[ai][bj][m][n], 0, 0, 0); \
;     __builtin_amdgcn_s_setprio(0); } while (0)
; template <int K, int LD = K>
; __device__ __forceinline__ void gemm_main(const GAS bf16* A, const GAS bf16* Bt, int brow, int bcol, f32x4 (&acc)[2][2][4][2]) {
;     ...
;     LDA(At, 1, 1); STAGE(SA(1, 0), pA0, 3);
;     BAR; WAIT_L(0); MMA(1, 0, At, B0); BAR; SCHED;
;     STAGE(SB(1, 1), pB1, 3);
;     WAIT_V(6); BAR; MMA(1, 1, At, B1); BAR;
;     pA0 += 4 * BK; pA1 += 4 * BK; pB0 += 4 * BK; pB1 += 4 * BK;
;     asm volatile("" : "+s"(pA0), "+s"(pA1), "+s"(pB0), "+s"(pB1));
;   }
;   { LDB(B0, 0, 0); LDA(At, 0, 0); STAGE(SA(1, 1), pA1, 1);
;     BAR; WAIT_L(0); MMA(0, 0, At, B0); BAR;
;     LDB(B1, 0, 1); BAR; WAIT_L(0); MMA(0, 1, At, B1); BAR;
	ds_read_b128 v[182:185], v139 offset:49152
	ds_read_b128 v[186:189], v139 offset:50176
	ds_read_b128 v[190:193], v138 offset:49152
	ds_read_b128 v[194:197], v138 offset:50176
	ds_read_b128 v[198:201], v137 offset:49152
	ds_read_b128 v[202:205], v137 offset:50176
	ds_read_b128 v[206:209], v136 offset:49152
	ds_read_b128 v[210:213], v136 offset:50176
	global_load_lds_dwordx4 v[168:169], off
	v_lshl_add_u64 v[168:169], v[238:239], 0, s[10:11]
	s_mov_b32 m0, s22
	s_nop 0
	global_load_lds_dwordx4 v[168:169], off
	s_barrier
	s_waitcnt lgkmcnt(0)
	s_waitcnt lgkmcnt(0)
	v_mfma_f32_16x16x32_bf16 v[62:65], v[160:163], v[182:185], v[62:65]
	v_mfma_f32_16x16x32_bf16 v[58:61], v[174:177], v[182:185], v[58:61]
	v_mfma_f32_16x16x32_bf16 v[54:57], v[160:163], v[190:193], v[54:57]
	v_mfma_f32_16x16x32_bf16 v[50:53], v[174:177], v[190:193], v[50:53]
	v_mfma_f32_16x16x32_bf16 v[46:49], v[160:163], v[198:201], v[46:49]
	v_mfma_f32_16x16x32_bf16 v[42:45], v[174:177], v[198:201], v[42:45]
	v_mfma_f32_16x16x32_bf16 v[38:41], v[160:163], v[206:209], v[38:41]
	v_mfma_f32_16x16x32_bf16 v[34:37], v[174:177], v[206:209], v[34:37]
	v_mfma_f32_16x16x32_bf16 v[62:65], v[164:167], v[186:189], v[62:65]
	v_mfma_f32_16x16x32_bf16 v[58:61], v[178:181], v[186:189], v[58:61]
	v_mfma_f32_16x16x32_bf16 v[54:57], v[164:167], v[194:197], v[54:57]
	v_mfma_f32_16x16x32_bf16 v[50:53], v[178:181], v[194:197], v[50:53]
	v_mfma_f32_16x16x32_bf16 v[46:49], v[164:167], v[202:205], v[46:49]
	v_mfma_f32_16x16x32_bf16 v[42:45], v[178:181], v[202:205], v[42:45]
	v_mfma_f32_16x16x32_bf16 v[38:41], v[164:167], v[210:213], v[38:41]
	v_mfma_f32_16x16x32_bf16 v[34:37], v[178:181], v[210:213], v[34:37]
	s_barrier
	v_readfirstlane_b32 s22, v158
	v_lshl_add_u64 v[160:161], v[240:241], 0, s[10:11]
	s_mov_b32 m0, s22
	v_readfirstlane_b32 s22, v159
	global_load_lds_dwordx4 v[160:161], off
	v_lshl_add_u64 v[160:161], v[242:243], 0, s[10:11]
	s_mov_b32 m0, s22
	s_nop 0
	global_load_lds_dwordx4 v[160:161], off
	s_waitcnt vmcnt(10)
	s_barrier
	v_mfma_f32_16x16x32_bf16 v[30:33], v[214:217], v[182:185], v[30:33]
	v_mfma_f32_16x16x32_bf16 v[26:29], v[222:225], v[182:185], v[26:29]
	v_mfma_f32_16x16x32_bf16 v[22:25], v[214:217], v[190:193], v[22:25]
	v_mfma_f32_16x16x32_bf16 v[18:21], v[222:225], v[190:193], v[18:21]
	v_mfma_f32_16x16x32_bf16 v[14:17], v[214:217], v[198:201], v[14:17]
	v_mfma_f32_16x16x32_bf16 v[10:13], v[222:225], v[198:201], v[10:13]
	v_mfma_f32_16x16x32_bf16 v[6:9], v[214:217], v[206:209], v[6:9]
	v_mfma_f32_16x16x32_bf16 v[2:5], v[222:225], v[206:209], v[2:5]
	v_mfma_f32_16x16x32_bf16 v[30:33], v[218:221], v[186:189], v[30:33]
	v_mfma_f32_16x16x32_bf16 v[26:29], v[226:229], v[186:189], v[26:29]
	v_mfma_f32_16x16x32_bf16 v[22:25], v[218:221], v[194:197], v[22:25]
	v_mfma_f32_16x16x32_bf16 v[18:21], v[226:229], v[194:197], v[18:21]
	v_mfma_f32_16x16x32_bf16 v[14:17], v[218:221], v[202:205], v[14:17]
	v_mfma_f32_16x16x32_bf16 v[10:13], v[226:229], v[202:205], v[10:13]
	v_mfma_f32_16x16x32_bf16 v[6:9], v[218:221], v[210:213], v[6:9]
	v_mfma_f32_16x16x32_bf16 v[2:5], v[226:229], v[210:213], v[2:5]
	s_add_i32 s15, s15, 2
	s_cmp_lt_u32 s15, 12
	s_barrier
	s_cbranch_scc1 .LBB0_884
	v_lshl_add_u64 v[198:199], s[12:13], 0, v[130:131]
	v_readfirstlane_b32 s15, v144
	v_lshl_add_u64 v[198:199], v[198:199], 0, s[6:7]
	s_mov_b32 m0, s15
	v_lshl_add_u64 v[132:133], s[12:13], 0, v[132:133]
	v_readfirstlane_b32 s12, v143
	ds_read_b128 v[146:149], v145
	ds_read_b128 v[150:153], v145 offset:1024
	ds_read_b128 v[154:157], v145 offset:2048
	ds_read_b128 v[158:161], v145 offset:3072
	ds_read_b128 v[162:165], v139
	ds_read_b128 v[166:169], v139 offset:1024
	ds_read_b128 v[174:177], v138
	ds_read_b128 v[178:181], v138 offset:1024
	ds_read_b128 v[182:185], v137
	ds_read_b128 v[186:189], v137 offset:1024
	ds_read_b128 v[190:193], v136
	ds_read_b128 v[194:197], v136 offset:1024
	global_load_lds_dwordx4 v[198:199], off
	v_lshl_add_u64 v[132:133], v[132:133], 0, s[6:7]
	s_mov_b32 m0, s12
	s_nop 0
	global_load_lds_dwordx4 v[132:133], off
	s_waitcnt vmcnt(10)
	s_barrier
	s_waitcnt lgkmcnt(0)
	s_waitcnt lgkmcnt(0)
	v_mfma_f32_16x16x32_bf16 v[126:129], v[146:149], v[162:165], v[126:129]
	v_mfma_f32_16x16x32_bf16 v[122:125], v[154:157], v[162:165], v[122:125]
	v_mfma_f32_16x16x32_bf16 v[110:113], v[146:149], v[182:185], v[110:113]
	v_mfma_f32_16x16x32_bf16 v[106:109], v[154:157], v[182:185], v[106:109]
	v_mfma_f32_16x16x32_bf16 v[126:129], v[150:153], v[166:169], v[126:129]
	v_mfma_f32_16x16x32_bf16 v[122:125], v[158:161], v[166:169], v[122:125]
	v_mfma_f32_16x16x32_bf16 v[118:121], v[146:149], v[174:177], v[118:121]
	v_mfma_f32_16x16x32_bf16 v[114:117], v[154:157], v[174:177], v[114:117]
	v_mfma_f32_16x16x32_bf16 v[110:113], v[150:153], v[186:189], v[110:113]
	v_mfma_f32_16x16x32_bf16 v[106:109], v[158:161], v[186:189], v[106:109]
	v_mfma_f32_16x16x32_bf16 v[102:105], v[146:149], v[190:193], v[102:105]
	v_mfma_f32_16x16x32_bf16 v[98:101], v[154:157], v[190:193], v[98:101]
	v_mfma_f32_16x16x32_bf16 v[198:201], v[150:153], v[178:181], v[118:121]
	v_mfma_f32_16x16x32_bf16 v[202:205], v[158:161], v[178:181], v[114:117]
	v_mfma_f32_16x16x32_bf16 v[206:209], v[150:153], v[194:197], v[102:105]
	v_mfma_f32_16x16x32_bf16 v[210:213], v[158:161], v[194:197], v[98:101]
	s_barrier
	s_nop 1
	ds_read_b128 v[98:101], v142
	ds_read_b128 v[102:105], v142 offset:1024
	ds_read_b128 v[114:117], v142 offset:2048
	ds_read_b128 v[118:121], v142 offset:3072
	s_waitcnt vmcnt(8)
	s_barrier
; #define WAIT_V(n) asm volatile("s_waitcnt vmcnt(" #n ")" ::: "memory")
; #define WAIT_L(n) asm volatile("s_waitcnt lgkmcnt(" #n ")" ::: "memory")
; #define BAR __builtin_amdgcn_s_barrier()
; #define LDA(dst, b, h) for (int m = 0; m < 4; ++m) for (int k = 0; k < 2; ++k) \
;     dst[m][k] = *reinterpret_cast<const bf16x8*>((char*)SA(b, h) + lds_byte(wr * 64 + m * 16 + fr, k * 32 + fq * 8))
; #define LDB(dst, b, h) for (int n = 0; n < 2; ++n) for (int k = 0; k < 2; ++k) \
;     dst[n][k] = *reinterpret_cast<const bf16x8*>((char*)SB(b, h) + lds_byte(wc * 32 + n * 16 + fr, k * 32 + fq * 8))
; #define MMA(ai, bj, At_, Bt_) do { __builtin_amdgcn_s_setprio(1); \
;     for (int m = 0; m < 4; ++m) for (int n = 0; n < 2; ++n) for (int k = 0; k < 2; ++k) \
;       acc[ai][bj][m][n] = __builtin_amdgcn_mfma_f32_16x16x32_bf16(At_[m][k], Bt_[n][k], acc[ai][bj][m][n], 0, 0, 0); \
;     __builtin_amdgcn_s_setprio(0); } while (0)
; template <int K, int LD = K>
; __device__ __forceinline__ void gemm_main(const GAS bf16* A, const GAS bf16* Bt, int brow, int bcol, f32x4 (&acc)[2][2][4][2]) {
;     ...
;     LDB(B1, 0, 1); BAR; WAIT_L(0); MMA(0, 1, At, B1); BAR;
;     LDA(At, 0, 1); WAIT_V(4); BAR; WAIT_L(0); MMA(1, 0, At, B0); MMA(1, 1, At, B1); BAR; }
;   { LDB(B0, 1, 0); LDA(At, 1, 0); WAIT_V(2); BAR; WAIT_L(0); MMA(0, 0, At, B0); BAR;
;     LDB(B1, 1, 1); WAIT_V(0); BAR; WAIT_L(0); MMA(0, 1, At, B1); BAR;
	s_waitcnt lgkmcnt(0)
	s_waitcnt lgkmcnt(0)
	v_mfma_f32_16x16x32_bf16 v[94:97], v[98:101], v[162:165], v[94:97]
	v_mfma_f32_16x16x32_bf16 v[90:93], v[114:117], v[162:165], v[90:93]
	v_mfma_f32_16x16x32_bf16 v[78:81], v[98:101], v[182:185], v[78:81]
	v_mfma_f32_16x16x32_bf16 v[74:77], v[114:117], v[182:185], v[74:77]
	v_mfma_f32_16x16x32_bf16 v[94:97], v[102:105], v[166:169], v[94:97]
	v_mfma_f32_16x16x32_bf16 v[90:93], v[118:121], v[166:169], v[90:93]
	v_mfma_f32_16x16x32_bf16 v[86:89], v[98:101], v[174:177], v[86:89]
	v_mfma_f32_16x16x32_bf16 v[82:85], v[114:117], v[174:177], v[82:85]
	v_mfma_f32_16x16x32_bf16 v[78:81], v[102:105], v[186:189], v[78:81]
	v_mfma_f32_16x16x32_bf16 v[74:77], v[118:121], v[186:189], v[74:77]
	v_mfma_f32_16x16x32_bf16 v[70:73], v[98:101], v[190:193], v[70:73]
	v_mfma_f32_16x16x32_bf16 v[66:69], v[114:117], v[190:193], v[66:69]
	v_mfma_f32_16x16x32_bf16 v[142:145], v[102:105], v[178:181], v[86:89]
	v_mfma_f32_16x16x32_bf16 v[162:165], v[118:121], v[178:181], v[82:85]
	v_mfma_f32_16x16x32_bf16 v[166:169], v[102:105], v[194:197], v[70:73]
	v_mfma_f32_16x16x32_bf16 v[174:177], v[118:121], v[194:197], v[66:69]
	s_barrier
	s_nop 1
	ds_read_b128 v[66:69], v139 offset:16384
	ds_read_b128 v[70:73], v139 offset:17408
	ds_read_b128 v[82:85], v138 offset:16384
	ds_read_b128 v[86:89], v138 offset:17408
	ds_read_b128 v[178:181], v137 offset:16384
	ds_read_b128 v[182:185], v137 offset:17408
	ds_read_b128 v[186:189], v136 offset:16384
	ds_read_b128 v[190:193], v136 offset:17408
	s_waitcnt vmcnt(4)
	s_barrier
	s_waitcnt lgkmcnt(0)
	s_waitcnt lgkmcnt(0)
	v_mfma_f32_16x16x32_bf16 v[62:65], v[146:149], v[66:69], v[62:65]
	v_mfma_f32_16x16x32_bf16 v[58:61], v[154:157], v[66:69], v[58:61]
	v_mfma_f32_16x16x32_bf16 v[46:49], v[146:149], v[178:181], v[46:49]
	v_mfma_f32_16x16x32_bf16 v[38:41], v[146:149], v[186:189], v[38:41]
	v_mfma_f32_16x16x32_bf16 v[62:65], v[150:153], v[70:73], v[62:65]
	v_mfma_f32_16x16x32_bf16 v[58:61], v[158:161], v[70:73], v[58:61]
	v_mfma_f32_16x16x32_bf16 v[54:57], v[146:149], v[82:85], v[54:57]
	v_mfma_f32_16x16x32_bf16 v[50:53], v[154:157], v[82:85], v[50:53]
	v_mfma_f32_16x16x32_bf16 v[46:49], v[150:153], v[182:185], v[46:49]
	v_mfma_f32_16x16x32_bf16 v[42:45], v[154:157], v[178:181], v[42:45]
	v_mfma_f32_16x16x32_bf16 v[38:41], v[150:153], v[190:193], v[38:41]
	v_mfma_f32_16x16x32_bf16 v[34:37], v[154:157], v[186:189], v[34:37]
	v_mfma_f32_16x16x32_bf16 v[194:197], v[150:153], v[86:89], v[54:57]
	v_mfma_f32_16x16x32_bf16 v[214:217], v[158:161], v[86:89], v[50:53]
	v_mfma_f32_16x16x32_bf16 v[218:221], v[158:161], v[182:185], v[42:45]
	v_mfma_f32_16x16x32_bf16 v[146:149], v[158:161], v[190:193], v[34:37]
	v_mfma_f32_16x16x32_bf16 v[30:33], v[98:101], v[66:69], v[30:33]
	v_mfma_f32_16x16x32_bf16 v[26:29], v[114:117], v[66:69], v[26:29]
	v_mfma_f32_16x16x32_bf16 v[14:17], v[98:101], v[178:181], v[14:17]
	v_mfma_f32_16x16x32_bf16 v[6:9], v[98:101], v[186:189], v[6:9]
	v_mfma_f32_16x16x32_bf16 v[30:33], v[102:105], v[70:73], v[30:33]
	v_mfma_f32_16x16x32_bf16 v[26:29], v[118:121], v[70:73], v[26:29]
	v_mfma_f32_16x16x32_bf16 v[22:25], v[98:101], v[82:85], v[22:25]
	v_mfma_f32_16x16x32_bf16 v[18:21], v[114:117], v[82:85], v[18:21]
	v_mfma_f32_16x16x32_bf16 v[14:17], v[102:105], v[182:185], v[14:17]
	v_mfma_f32_16x16x32_bf16 v[10:13], v[114:117], v[178:181], v[10:13]
	v_mfma_f32_16x16x32_bf16 v[6:9], v[102:105], v[190:193], v[6:9]
	v_mfma_f32_16x16x32_bf16 v[2:5], v[114:117], v[186:189], v[2:5]
	v_mfma_f32_16x16x32_bf16 v[150:153], v[102:105], v[86:89], v[22:25]
	v_mfma_f32_16x16x32_bf16 v[154:157], v[118:121], v[86:89], v[18:21]
	v_mfma_f32_16x16x32_bf16 v[158:161], v[118:121], v[182:185], v[10:13]
	v_mfma_f32_16x16x32_bf16 v[178:181], v[118:121], v[190:193], v[2:5]
	s_barrier
	s_nop 1
	ds_read_b128 v[2:5], v141
	ds_read_b128 v[10:13], v141 offset:1024
	ds_read_b128 v[182:185], v141 offset:2048
	ds_read_b128 v[186:189], v141 offset:3072
	ds_read_b128 v[18:21], v139 offset:32768
	ds_read_b128 v[22:25], v139 offset:33792
	ds_read_b128 v[34:37], v138 offset:32768
	ds_read_b128 v[42:45], v138 offset:33792
	ds_read_b128 v[50:53], v137 offset:32768
	ds_read_b128 v[54:57], v137 offset:33792
	ds_read_b128 v[190:193], v136 offset:32768
	ds_read_b128 v[222:225], v136 offset:33792
	s_waitcnt vmcnt(2)
	s_barrier
	s_waitcnt lgkmcnt(0)
	s_waitcnt lgkmcnt(0)
	v_mfma_f32_16x16x32_bf16 v[66:69], v[2:5], v[18:21], v[126:129]
	v_mfma_f32_16x16x32_bf16 v[118:121], v[10:13], v[22:25], v[66:69]
	v_mfma_f32_16x16x32_bf16 v[66:69], v[182:185], v[18:21], v[122:125]
	v_mfma_f32_16x16x32_bf16 v[114:117], v[186:189], v[22:25], v[66:69]
	v_mfma_f32_16x16x32_bf16 v[66:69], v[2:5], v[34:37], v[198:201]
	v_mfma_f32_16x16x32_bf16 v[102:105], v[10:13], v[42:45], v[66:69]
	v_mfma_f32_16x16x32_bf16 v[66:69], v[182:185], v[34:37], v[202:205]
	v_mfma_f32_16x16x32_bf16 v[98:101], v[186:189], v[42:45], v[66:69]
	v_mfma_f32_16x16x32_bf16 v[66:69], v[2:5], v[50:53], v[110:113]
	v_mfma_f32_16x16x32_bf16 v[86:89], v[10:13], v[54:57], v[66:69]
	v_mfma_f32_16x16x32_bf16 v[66:69], v[182:185], v[50:53], v[106:109]
	v_mfma_f32_16x16x32_bf16 v[82:85], v[186:189], v[54:57], v[66:69]
	v_mfma_f32_16x16x32_bf16 v[66:69], v[2:5], v[190:193], v[206:209]
	v_mfma_f32_16x16x32_bf16 v[70:73], v[10:13], v[222:225], v[66:69]
	v_mfma_f32_16x16x32_bf16 v[66:69], v[182:185], v[190:193], v[210:213]
	v_mfma_f32_16x16x32_bf16 v[66:69], v[186:189], v[222:225], v[66:69]
	s_barrier
	ds_read_b128 v[198:201], v140
	ds_read_b128 v[202:205], v140 offset:1024
	ds_read_b128 v[206:209], v140 offset:2048
	ds_read_b128 v[210:213], v140 offset:3072
	s_waitcnt vmcnt(0)
	s_barrier
; #define WAIT_V(n) asm volatile("s_waitcnt vmcnt(" #n ")" ::: "memory")
; #define WAIT_L(n) asm volatile("s_waitcnt lgkmcnt(" #n ")" ::: "memory")
; #define BAR __builtin_amdgcn_s_barrier()
; #define LDA(dst, b, h) for (int m = 0; m < 4; ++m) for (int k = 0; k < 2; ++k) \
;     dst[m][k] = *reinterpret_cast<const bf16x8*>((char*)SA(b, h) + lds_byte(wr * 64 + m * 16 + fr, k * 32 + fq * 8))
; #define LDB(dst, b, h) for (int n = 0; n < 2; ++n) for (int k = 0; k < 2; ++k) \
;     dst[n][k] = *reinterpret_cast<const bf16x8*>((char*)SB(b, h) + lds_byte(wc * 32 + n * 16 + fr, k * 32 + fq * 8))
; #define MMA(ai, bj, At_, Bt_) do { __builtin_amdgcn_s_setprio(1); \
;     for (int m = 0; m < 4; ++m) for (int n = 0; n < 2; ++n) for (int k = 0; k < 2; ++k) \
;       acc[ai][bj][m][n] = __builtin_amdgcn_mfma_f32_16x16x32_bf16(At_[m][k], Bt_[n][k], acc[ai][bj][m][n], 0, 0, 0); \
;     __builtin_amdgcn_s_setprio(0); } while (0)
; template <int K, int LD = K>
; __device__ __forceinline__ void gemm_main(const GAS bf16* A, const GAS bf16* Bt, int brow, int bcol, f32x4 (&acc)[2][2][4][2]) {
;     ...
;   { LDB(B0, 1, 0); LDA(At, 1, 0); WAIT_V(2); BAR; WAIT_L(0); MMA(0, 0, At, B0); BAR;
;     LDB(B1, 1, 1); WAIT_V(0); BAR; WAIT_L(0); MMA(0, 1, At, B1); BAR;
;     LDA(At, 1, 1); BAR; WAIT_L(0); MMA(1, 0, At, B0); MMA(1, 1, At, B1); BAR; }
;   if (wr == 0) BAR;
	s_waitcnt lgkmcnt(0)
	s_waitcnt lgkmcnt(0)
	v_mfma_f32_16x16x32_bf16 v[94:97], v[198:201], v[18:21], v[94:97]
	v_mfma_f32_16x16x32_bf16 v[18:21], v[206:209], v[18:21], v[90:93]
	v_mfma_f32_16x16x32_bf16 v[122:125], v[210:213], v[22:25], v[18:21]
	v_mfma_f32_16x16x32_bf16 v[18:21], v[198:201], v[34:37], v[142:145]
	v_mfma_f32_16x16x32_bf16 v[110:113], v[202:205], v[42:45], v[18:21]
	v_mfma_f32_16x16x32_bf16 v[18:21], v[206:209], v[34:37], v[162:165]
	v_mfma_f32_16x16x32_bf16 v[106:109], v[210:213], v[42:45], v[18:21]
	v_mfma_f32_16x16x32_bf16 v[18:21], v[198:201], v[50:53], v[78:81]
	v_mfma_f32_16x16x32_bf16 v[126:129], v[202:205], v[22:25], v[94:97]
	v_mfma_f32_16x16x32_bf16 v[94:97], v[202:205], v[54:57], v[18:21]
	v_mfma_f32_16x16x32_bf16 v[18:21], v[206:209], v[50:53], v[74:77]
	v_mfma_f32_16x16x32_bf16 v[90:93], v[210:213], v[54:57], v[18:21]
	v_mfma_f32_16x16x32_bf16 v[18:21], v[198:201], v[190:193], v[166:169]
	v_mfma_f32_16x16x32_bf16 v[78:81], v[202:205], v[222:225], v[18:21]
	v_mfma_f32_16x16x32_bf16 v[18:21], v[206:209], v[190:193], v[174:177]
	v_mfma_f32_16x16x32_bf16 v[74:77], v[210:213], v[222:225], v[18:21]
	s_barrier
	ds_read_b128 v[140:143], v139 offset:49152
	ds_read_b128 v[162:165], v139 offset:50176
	ds_read_b128 v[166:169], v138 offset:49152
	ds_read_b128 v[174:177], v138 offset:50176
	ds_read_b128 v[190:193], v137 offset:49152
	ds_read_b128 v[222:225], v137 offset:50176
	ds_read_b128 v[226:229], v136 offset:49152
	ds_read_b128 v[136:139], v136 offset:50176
	s_barrier
	s_waitcnt lgkmcnt(0)
	s_waitcnt lgkmcnt(0)
	v_mfma_f32_16x16x32_bf16 v[18:21], v[2:5], v[140:143], v[62:65]
	v_mfma_f32_16x16x32_bf16 v[54:57], v[10:13], v[162:165], v[18:21]
	v_mfma_f32_16x16x32_bf16 v[18:21], v[182:185], v[140:143], v[58:61]
	v_mfma_f32_16x16x32_bf16 v[50:53], v[186:189], v[162:165], v[18:21]
	v_mfma_f32_16x16x32_bf16 v[18:21], v[2:5], v[166:169], v[194:197]
	v_mfma_f32_16x16x32_bf16 v[42:45], v[10:13], v[174:177], v[18:21]
	v_mfma_f32_16x16x32_bf16 v[18:21], v[182:185], v[166:169], v[214:217]
	v_mfma_f32_16x16x32_bf16 v[34:37], v[186:189], v[174:177], v[18:21]
	v_mfma_f32_16x16x32_bf16 v[18:21], v[2:5], v[190:193], v[46:49]
	v_mfma_f32_16x16x32_bf16 v[2:5], v[2:5], v[226:229], v[38:41]
	v_mfma_f32_16x16x32_bf16 v[22:25], v[10:13], v[222:225], v[18:21]
	v_mfma_f32_16x16x32_bf16 v[18:21], v[182:185], v[190:193], v[218:221]
	v_mfma_f32_16x16x32_bf16 v[10:13], v[10:13], v[136:139], v[2:5]
	v_mfma_f32_16x16x32_bf16 v[2:5], v[182:185], v[226:229], v[146:149]
	v_mfma_f32_16x16x32_bf16 v[18:21], v[186:189], v[222:225], v[18:21]
	v_mfma_f32_16x16x32_bf16 v[2:5], v[186:189], v[136:139], v[2:5]
	v_mfma_f32_16x16x32_bf16 v[26:29], v[206:209], v[140:143], v[26:29]
	v_mfma_f32_16x16x32_bf16 v[30:33], v[198:201], v[140:143], v[30:33]
	v_mfma_f32_16x16x32_bf16 v[58:61], v[210:213], v[162:165], v[26:29]
	v_mfma_f32_16x16x32_bf16 v[26:29], v[198:201], v[166:169], v[150:153]
	v_mfma_f32_16x16x32_bf16 v[14:17], v[198:201], v[190:193], v[14:17]
	v_mfma_f32_16x16x32_bf16 v[62:65], v[202:205], v[162:165], v[30:33]
	v_mfma_f32_16x16x32_bf16 v[46:49], v[202:205], v[174:177], v[26:29]
	v_mfma_f32_16x16x32_bf16 v[26:29], v[206:209], v[166:169], v[154:157]
	v_mfma_f32_16x16x32_bf16 v[30:33], v[202:205], v[222:225], v[14:17]
	v_mfma_f32_16x16x32_bf16 v[14:17], v[206:209], v[190:193], v[158:161]
	v_mfma_f32_16x16x32_bf16 v[6:9], v[198:201], v[226:229], v[6:9]
	v_mfma_f32_16x16x32_bf16 v[38:41], v[210:213], v[174:177], v[26:29]
	v_mfma_f32_16x16x32_bf16 v[26:29], v[210:213], v[222:225], v[14:17]
	v_mfma_f32_16x16x32_bf16 v[14:17], v[202:205], v[136:139], v[6:9]
	v_mfma_f32_16x16x32_bf16 v[6:9], v[206:209], v[226:229], v[178:181]
	v_mfma_f32_16x16x32_bf16 v[6:9], v[210:213], v[136:139], v[6:9]
	v_cmp_gt_u32_e32 vcc, s34, v135
	s_barrier
	s_and_saveexec_b64 s[12:13], vcc
	s_cbranch_execz .LBB0_887
	s_barrier
; #define GAS __attribute__((address_space(1)))
; __device__ __forceinline__ int otid() { int t = threadIdx.x; asm volatile("" : "+v"(t)); return t; }
; #define STAGE(P, GP, ktrel) do { const GAS char* _g = (GP) + (ktrel) * (BK * 2); \
;     __builtin_amdgcn_global_load_lds((const GAS unsigned*)(_g + so0), (unsigned*)((char*)(P) + tid_ * 16), 16, 0, 0); \
;     __builtin_amdgcn_global_load_lds((const GAS unsigned*)(_g + so1), (unsigned*)((char*)(P) + tid_ * 16 + 8192), 16, 0, 0); } while (0)
; template <int K, int LD = K>
; __device__ __forceinline__ void gemm_prefetch(const GAS bf16* A, const GAS bf16* Bt, int brow, int bcol) {
;   bf16* shm = (bf16*)smem_raw;
;   const int tid_ = otid();
;   unsigned so0, so1;
;   { int r_, c_; stage_rc(tid_ * 16, r_, c_); so0 = (unsigned)(r_ * LD + c_) * 2u; stage_rc(tid_ * 16 + 8192, r_, c_); so1 = (unsigned)(r_ * LD + c_) * 2u; }
;   const GAS char* pA0 = (const GAS char*)A + (long)brow * LD * 2; const GAS char* pA1 = pA0 + (long)HALF * LD * 2;
;   const GAS char* pB0 = (const GAS char*)Bt + (long)bcol * LD * 2; const GAS char* pB1 = pB0 + (long)HALF * LD * 2;
;   asm volatile("" : "+s"(pA0), "+s"(pA1), "+s"(pB0), "+s"(pB1));
;   STAGE(SB(0, 0), pB0, 0); STAGE(SA(0, 0), pA0, 0);
;   STAGE(SB(0, 1), pB1, 0); STAGE(SA(0, 1), pA1, 0);
;   STAGE(SB(1, 0), pB0, 1); STAGE(SA(1, 0), pA0, 1); STAGE(SB(1, 1), pB1, 1);
; }
; __device__ __forceinline__ void load_rr(const GAS float* ssq, int brow, int par) {
;   float* rr = (float*)(smem_raw + LDS_RR) + par * 256;
;   const int tx = otid();
;   if (tx < 256) {
;     const GAS f32x4* s = (const GAS f32x4*)(ssq + (size_t)(brow + tx) * 16);
;     f32x4 a = s[0], b = s[1], c = s[2], d = s[3];
;     float t = ((a.x + a.y) + (a.z + a.w)) + ((b.x + b.y) + (b.z + b.w)) + ((c.x + c.y) + (c.z + c.w)) + ((d.x + d.y) + (d.z + d.w));
;     rr[tx] = rsqrtf(t * (1.f / DM) + EPS);
;   }
.LBB0_887:
	s_or_b64 exec, exec, s[12:13]
	v_readfirstlane_b32 s12, v171
	s_add_i32 s3, s12, s3
	s_cmpk_gt_i32 s3, 0x57f
	s_cselect_b64 s[12:13], -1, 0
	s_and_b64 vcc, exec, s[12:13]
	s_mov_b32 s20, s41
	s_cbranch_vccnz .LBB0_880
	v_mov_b32_e32 v130, v170
	s_mul_hi_i32 s15, s3, 0x2e8ba2e9
	v_ashrrev_i32_e32 v132, 31, v130
	v_lshrrev_b32_e32 v132, 26, v132
	v_lshlrev_b32_e32 v135, 4, v130
	v_add_u32_e32 v132, v130, v132
	v_bfe_i32 v130, v130, 27, 1
	v_lshrrev_b32_e32 v130, 22, v130
	v_add_u32_e32 v130, v135, v130
	v_and_b32_e32 v130, 0xfffffc00, v130
	v_sub_u32_e32 v130, v135, v130
	v_lshrrev_b32_e32 v133, 4, v130
	v_bitop3_b32 v133, v133, v130, 32 bitop3:0x6c
	v_ashrrev_i32_e32 v130, 31, v130
	v_lshrrev_b32_e32 v130, 26, v130
	v_add_u32_e32 v130, v133, v130
	v_ashrrev_i32_e32 v130, 6, v130
	v_ashrrev_i32_e32 v132, 6, v132
	v_mul_i32_i24_e32 v137, 64, v130
	v_lshlrev_b32_e32 v136, 3, v132
	v_lshlrev_b32_e32 v132, 5, v132
	v_sub_u32_e32 v133, v133, v137
	s_lshr_b32 s16, s15, 31
	s_ashr_i32 s15, s15, 5
	v_and_b32_e32 v136, 0x1ffff0, v136
	v_and_b32_e32 v132, 32, v132
	v_ashrrev_i16_sdwa v133, v1, sext(v133) dst_sel:DWORD dst_unused:UNUSED_PAD src0_sel:DWORD src1_sel:BYTE_0
	s_add_i32 s15, s15, s16
	v_add_u32_sdwa v132, v132, sext(v133) dst_sel:DWORD dst_unused:UNUSED_PAD src0_sel:DWORD src1_sel:WORD_0
	v_add_lshl_u32 v130, v130, v136, 11
	s_mul_i32 s16, s15, 0xb0
	v_lshl_add_u32 v130, v132, 1, v130
	v_add_u32_e32 v132, 0x2000, v135
	s_sub_i32 s16, s3, s16
	v_ashrrev_i32_e32 v133, 31, v132
	s_lshl_b32 s15, s15, 3
	s_and_b32 s17, s16, 7
	v_lshrrev_b32_e32 v133, 22, v133
	s_or_b32 s28, s17, s15
	v_add_u32_e32 v133, v132, v133
	s_ashr_i32 s20, s16, 3
	s_lshl_b32 s16, s28, 8
	v_ashrrev_i32_e32 v133, 10, v133
	v_mul_i32_i24_e32 v136, 0x400, v133
	s_ashr_i32 s17, s16, 31
	s_lshl_b32 s18, s20, 8
	v_sub_u32_e32 v132, v132, v136
	s_lshl_b64 s[22:23], s[16:17], 11
	v_lshrrev_b32_e32 v136, 4, v132
	s_add_u32 s22, s26, s22
	v_bitop3_b32 v132, v136, v132, 32 bitop3:0x6c
	s_addc_u32 s23, s27, s23
	v_ashrrev_i32_e32 v137, 31, v132
	s_add_u32 s42, s22, 0x40000
	v_lshrrev_b32_e32 v137, 26, v137
	s_addc_u32 s43, s23, 0
	s_ashr_i32 s19, s18, 31
	v_add_u32_e32 v137, v132, v137
	s_lshl_b64 s[18:19], s[18:19], 11
	v_lshrrev_b32_e32 v138, 6, v137
	v_and_b32_e32 v137, 0xc0, v137
	s_add_u32 s18, s24, s18
	v_lshlrev_b32_e32 v136, 3, v133
	v_lshlrev_b32_e32 v133, 5, v133
	v_sub_u32_e32 v132, v132, v137
	s_addc_u32 s19, s25, s19
	v_add_u32_e32 v140, s29, v135
	v_and_b32_e32 v136, 0x1ffff0, v136
	v_and_b32_e32 v133, 32, v133
	v_ashrrev_i16_sdwa v132, v1, sext(v132) dst_sel:DWORD dst_unused:UNUSED_PAD src0_sel:DWORD src1_sel:BYTE_0
	s_add_u32 s44, s18, 0x40000
	v_readfirstlane_b32 s15, v140
	v_add_u32_e32 v140, 0x2000, v140
	v_add_u32_sdwa v132, v133, sext(v132) dst_sel:DWORD dst_unused:UNUSED_PAD src0_sel:DWORD src1_sel:WORD_0
	v_add_lshl_u32 v133, v138, v136, 11
	s_addc_u32 s45, s19, 0
	s_mov_b32 m0, s15
	v_readfirstlane_b32 s15, v140
	v_add_u32_e32 v148, 0x100, v135
	v_lshl_add_u32 v132, v132, 1, v133
	v_add_u32_e32 v144, 0x2000, v148
	global_load_lds_dwordx4 v130, s[18:19]
	s_mov_b32 m0, s15
	v_readfirstlane_b32 s15, v148
	v_mov_b32_e32 v133, v131
	global_load_lds_dwordx4 v132, s[18:19]
	s_mov_b32 m0, s15
	v_readfirstlane_b32 s15, v144
	v_add_u32_e32 v149, s30, v135
	v_lshl_add_u64 v[138:139], s[18:19], 0, v[132:133]
	global_load_lds_dwordx4 v130, s[22:23]
	v_lshl_add_u64 v[142:143], s[22:23], 0, v[132:133]
	s_mov_b32 m0, s15
	v_readfirstlane_b32 s15, v149
	v_lshl_add_u64 v[146:147], s[44:45], 0, v[132:133]
	v_add_u32_e32 v133, 0x2000, v149
	global_load_lds_dwordx4 v132, s[22:23]
	s_mov_b32 m0, s15
	v_readfirstlane_b32 s15, v133
	v_add_u32_e32 v133, 0x4000, v148
	global_load_lds_dwordx4 v130, s[44:45]
	s_mov_b32 m0, s15
	v_readfirstlane_b32 s15, v133
	global_load_lds_dwordx4 v132, s[44:45]
	s_mov_b32 m0, s15
	v_lshl_add_u64 v[136:137], s[18:19], 0, v[130:131]
	v_lshl_add_u64 v[140:141], s[22:23], 0, v[130:131]
	v_lshl_add_u64 v[144:145], s[44:45], 0, v[130:131]
	global_load_lds_dwordx4 v130, s[42:43]
	v_add_u32_e32 v130, 0x6000, v148
	s_nop 0
	v_readfirstlane_b32 s15, v130
	v_add_u32_e32 v130, s31, v135
	s_mov_b32 m0, s15
	v_readfirstlane_b32 s15, v130
	v_add_u32_e32 v130, 0x2000, v130
	global_load_lds_dwordx4 v132, s[42:43]
	v_lshl_add_u64 v[132:133], v[136:137], 0, s[6:7]
	s_mov_b32 m0, s15
	v_readfirstlane_b32 s15, v130
	v_add_u32_e32 v130, 0x8000, v148
	global_load_lds_dwordx4 v[132:133], off
	v_lshl_add_u64 v[132:133], v[138:139], 0, s[6:7]
	s_mov_b32 m0, s15
	v_readfirstlane_b32 s15, v130
	v_add_u32_e32 v130, 0xa000, v148
	global_load_lds_dwordx4 v[132:133], off
	v_lshl_add_u64 v[132:133], v[140:141], 0, s[6:7]
	s_mov_b32 m0, s15
	v_readfirstlane_b32 s15, v130
	v_add_u32_e32 v130, s33, v135
	global_load_lds_dwordx4 v[132:133], off
	v_lshl_add_u64 v[132:133], v[142:143], 0, s[6:7]
	s_mov_b32 m0, s15
	v_readfirstlane_b32 s15, v130
	v_add_u32_e32 v130, 0x2000, v130
	global_load_lds_dwordx4 v[132:133], off
	v_lshl_add_u64 v[132:133], v[144:145], 0, s[6:7]
	s_mov_b32 m0, s15
	v_readfirstlane_b32 s15, v130
	global_load_lds_dwordx4 v[132:133], off
	v_lshl_add_u64 v[132:133], v[146:147], 0, s[6:7]
	s_mov_b32 m0, s15
	v_mov_b32_e32 v130, v170
	global_load_lds_dwordx4 v[132:133], off
	s_nop 0
	v_cmp_gt_i32_e32 vcc, s34, v130
	s_and_saveexec_b64 s[18:19], vcc
	s_cbranch_execz .LBB0_879
	v_add_u32_e32 v132, s16, v130
	v_ashrrev_i32_e32 v133, 31, v132
	v_lshlrev_b64 v[132:133], 6, v[132:133]
	v_lshl_add_u64 v[132:133], s[4:5], 0, v[132:133]
	global_load_dwordx4 v[136:139], v[132:133], off
	global_load_dwordx4 v[140:143], v[132:133], off offset:16
	global_load_dwordx4 v[144:147], v[132:133], off offset:32
	global_load_dwordx4 v[148:151], v[132:133], off offset:48
	s_branch .LBB0_879
